# w_in GEMM epilogue: gate-bias loads hoisted per tile, rope-table loads per row block hoisted/prefetched with counted waits (no per-chunk load+drain)
# speedup vs baseline: 1.0087x; 1.0087x over previous
;     __device__ __forceinline__ void operator()(const f32x4 (&acc)[2][2][4][2], const Unit& u, int wr, int wc, int fr, int fq) const {
;         const int row0 = u.pm * BM + wr * 64 + fr, pn = u.pn, cw = wc * 32 + 8 * fq;
;         float rs[2][4];
; #pragma unroll
;         for (int ai = 0; ai < 2; ++ai)
; #pragma unroll
;             for (int m = 0; m < 4; ++m) rs[ai][m] = 1.f;
;         if constexpr (MODE == EP_IN || MODE == EP_U) {
;             const EGAS float* rsp = WSF(WS_RSTD) + row0;
; #pragma unroll
;             for (int ai = 0; ai < 2; ++ai)
; #pragma unroll
;                 for (int m = 0; m < 4; ++m) rs[ai][m] = rsp[ai * HALF + m * 16];
;         }
; #pragma unroll
;         for (int ai = 0; ai < 2; ++ai)
; #pragma unroll
;             for (int m = 0; m < 4; ++m) {
;                 const unsigned row = (unsigned)(row0 + ai * HALF + m * 16);
; #pragma unroll
;                 for (int bj = 0; bj < 2; ++bj) {
;                     f32x4 v0 = acc[ai][bj][m][0], v1 = acc[ai][bj][m][1];
;                     if constexpr (MODE == EP_IN || MODE == EP_U) { v0 = v0 * rs[ai][m]; v1 = v1 * rs[ai][m]; }
;                     const int ct = bj * HALF + cw;
;                     if constexpr (MODE == EP_IN) {
;                         if (pn < 12) {
;                             rope8(v0, v1, WSF(WS_ROPEA) + (row * 64 + (cw >> 1)) * 2);
;                             EGAS bf16_t* O = pn < 6 ? WSB(WS_QA) : WSB(WS_KA); const int c = (pn < 6 ? pn : pn - 6) * 256 + ct;
;                             st8(O + row * WA + c, v0, v1);
;                         } else if (pn < 18) { st8(WSB(WS_VA) + row * WA + (pn - 12) * 256 + ct, v0, v1);
;                         } else if (pn < 20) { st8(WSB(WS_QL) + row * QLORA + (pn - 18) * 256 + ct, v0, v1);
;                         } else if (pn < 22) { st8(WSB(WS_KVL) + row * KVLORA + (pn - 20) * 256 + ct, v0, v1);
;                         } else if (pn < 38) {
;                             const int gc = (pn - 22) * 256 + ct; const EGAS float* bg = (const EGAS float*)p.f0; const f32x4 b0 = *(const EGAS f32x4*)(bg + gc), b1 = *(const EGAS f32x4*)(bg + gc + 4);
; #pragma unroll
;                             for (int e = 0; e < 4; ++e) { v0[e] = sigm(v0[e] + b0[e]); v1[e] = sigm(v1[e] + b1[e]); }
;                             st8f8(WS8(WS_GATES) + row * 4096 + gc, v0, v1);
;                         } else {
.LBB0_336:
	v_lshl_add_u32 v150, s26, 8, v141
	v_ashrrev_i32_e32 v151, 31, v150
	v_lshl_add_u64 v[148:149], v[150:151], 2, s[50:51]
	global_load_dword v176, v[148:149], off
	global_load_dword v162, v[148:149], off offset:64
	global_load_dword v160, v[148:149], off offset:128
	global_load_dword v158, v[148:149], off offset:192
	global_load_dword v156, v[148:149], off offset:512
	global_load_dword v154, v[148:149], off offset:576
	global_load_dword v152, v[148:149], off offset:640
	s_nop 0
	global_load_dword v148, v[148:149], off offset:704
	s_cmp_gt_i32 s24, 11
	s_cselect_b64 s[42:43], -1, 0
	s_cmp_gt_u32 s24, 17
	s_cselect_b64 s[36:37], -1, 0
	s_cmp_gt_u32 s24, 19
	s_cselect_b64 s[30:31], -1, 0
	s_cmp_gt_u32 s24, 21
	s_cselect_b64 s[28:29], -1, 0
	s_cmp_lt_u32 s24, 38
	s_cselect_b64 s[26:27], -1, 0
	s_cmp_gt_u32 s24, 37
	s_cselect_b64 s[34:35], -1, 0
	s_lshl_b32 s74, s24, 8
	s_movk_i32 s17, 0x600
	s_add_i32 s19, s74, 0xffffea00
	s_add_i32 s25, s74, 0xfffffa00
	v_mul_lo_u32 v164, v150, s17
	s_cmp_lt_i32 s24, 6
	s_mov_b32 s17, 0xd200000
	v_mov_b32_e32 v175, v1
	v_mov_b32_e32 v165, v1
	s_mov_b64 s[44:45], -1
	v_lshlrev_b32_e32 v0, 12, v150
	v_lshlrev_b32_e32 v174, 9, v150
	s_cselect_b32 s17, s17, 0x10200000
	s_cselect_b32 s24, s74, s25
	s_and_b64 vcc, s[28:29], s[26:27]
	s_cbranch_vccz .Lin_nogate_0
	v_or_b32_e32 v232, s19, v138
	v_mov_b32_e32 v233, v1
	v_lshl_add_u64 v[232:233], v[232:233], 2, s[10:11]
	global_load_dwordx4 v[216:219], v[232:233], off
	global_load_dwordx4 v[220:223], v[232:233], off offset:16
	global_load_dwordx4 v[224:227], v[232:233], off offset:512
	global_load_dwordx4 v[228:231], v[232:233], off offset:528
.Lin_nogate_0:
	s_and_b64 vcc, exec, s[42:43]
	s_cbranch_vccnz .Lin_norope_0
	v_lshl_or_b32 v248, v150, 7, v138
	v_lshlrev_b32_e32 v248, 2, v248
	global_load_dwordx4 v[216:219], v248, s[62:63]
	global_load_dwordx4 v[220:223], v248, s[62:63] offset:16
	v_add_u32_e32 v249, 0x2000, v248
	global_load_dwordx4 v[224:227], v249, s[62:63]
	global_load_dwordx4 v[228:231], v249, s[62:63] offset:16
	v_add_u32_e32 v249, 0x4000, v248
	global_load_dwordx4 v[232:235], v249, s[62:63]
	global_load_dwordx4 v[236:239], v249, s[62:63] offset:16
	v_add_u32_e32 v249, 0x6000, v248
	global_load_dwordx4 v[240:243], v249, s[62:63]
	global_load_dwordx4 v[244:247], v249, s[62:63] offset:16
.Lin_norope_0:
	s_and_b64 vcc, exec, s[42:43]
	s_waitcnt vmcnt(0)
	v_pk_mul_f32 v[128:129], v[128:129], v[176:177] op_sel_hi:[1,0]
	v_pk_mul_f32 v[178:179], v[126:127], v[176:177] op_sel_hi:[1,0]
	v_pk_mul_f32 v[124:125], v[124:125], v[176:177] op_sel_hi:[1,0]
	v_pk_mul_f32 v[126:127], v[122:123], v[176:177] op_sel_hi:[1,0]
	s_cbranch_vccz .LBB0_356
	s_and_b64 vcc, exec, s[36:37]
	s_cbranch_vccz .LBB0_353
	s_and_b64 vcc, exec, s[30:31]
	s_cbranch_vccz .LBB0_350
	s_and_b64 vcc, exec, s[28:29]
	s_cbranch_vccz .LBB0_347
	s_and_b64 vcc, exec, s[34:35]
	s_cbranch_vccz .LBB0_344
	v_readlane_b32 s44, v255, 55
	v_readlane_b32 s45, v255, 56
	s_andn2_b64 vcc, exec, s[44:45]
	s_cbranch_vccnz .LBB0_343
	v_lshlrev_b32_e32 v122, 6, v150
	v_readlane_b32 s44, v255, 53
	v_or_b32_e32 v180, v122, v138
	v_mov_b32_e32 v181, v1
	v_readlane_b32 s45, v255, 54
	v_mov_b32_e32 v123, v1
	v_lshl_add_u64 v[122:123], v[142:143], 0, v[122:123]
	v_lshl_add_u64 v[180:181], v[180:181], 2, s[44:45]
	global_load_dwordx4 v[184:187], v[180:181], off offset:16
	global_load_dwordx4 v[208:211], v[180:181], off
	s_waitcnt vmcnt(0)
	v_pk_mul_f32 v[180:181], v[128:129], v[210:211]
	s_nop 0
	v_sub_f32_e32 v153, v180, v181
	v_pk_mul_f32 v[180:181], v[128:129], v[210:211] op_sel:[1,0] op_sel_hi:[0,1]
	v_pk_mul_f32 v[212:213], v[178:179], v[208:209]
	v_pk_mul_f32 v[208:209], v[178:179], v[208:209] op_sel:[1,0] op_sel_hi:[0,1]
	v_add_f32_e32 v155, v180, v181
	v_pk_mul_f32 v[180:181], v[124:125], v[186:187]
	v_add_f32_e32 v151, v208, v209
	v_pk_mul_f32 v[208:209], v[126:127], v[184:185]
	v_pk_mul_f32 v[184:185], v[126:127], v[184:185] op_sel:[1,0] op_sel_hi:[0,1]
	v_sub_f32_e32 v161, v180, v181
	v_pk_mul_f32 v[180:181], v[124:125], v[186:187] op_sel:[1,0] op_sel_hi:[0,1]
	v_sub_f32_e32 v149, v212, v213
	v_sub_f32_e32 v157, v208, v209
	v_add_f32_e32 v159, v184, v185
	v_add_f32_e32 v163, v180, v181
	v_mov_b32_e32 v180, v1
	v_mov_b32_e32 v181, v1
	v_cvt_pk_fp8_f32 v180, v149, v151
	v_cvt_pk_fp8_f32 v181, v157, v159
	v_cvt_pk_fp8_f32 v180, v153, v155 op_sel:[0,0,1]
	v_cvt_pk_fp8_f32 v181, v161, v163 op_sel:[0,0,1]
	global_store_dwordx2 v[122:123], v[180:181], off

; #define EGAS __attribute__((address_space(1)))
; __device__ __forceinline__ float sigm(float x) { return __builtin_amdgcn_rcpf(1.f + __expf(-x)); }
;     __device__ __forceinline__ void operator()(const f32x4 (&acc)[2][2][4][2], const Unit& u, int wr, int wc, int fr, int fq) const {
;     ...
;                         } else if (pn < 38) {
;                             const int gc = (pn - 22) * 256 + ct; const EGAS float* bg = (const EGAS float*)p.f0; const f32x4 b0 = *(const EGAS f32x4*)(bg + gc), b1 = *(const EGAS f32x4*)(bg + gc + 4);
; #pragma unroll
;                             for (int e = 0; e < 4; ++e) { v0[e] = sigm(v0[e] + b0[e]); v1[e] = sigm(v1[e] + b1[e]); }
;                             st8f8(WS8(WS_GATES) + row * 4096 + gc, v0, v1);
.LBB0_344:
	s_andn2_b64 vcc, exec, s[44:45]
	s_cbranch_vccnz .LBB0_346
	v_or_b32_e32 v122, s19, v138
	v_mov_b32_e32 v123, v1
	v_mov_b32_e32 v180, v1
	v_mov_b32_e32 v181, v1
	v_add_f32_e32 v149, v178, v216
	v_add_f32_e32 v151, v126, v220
	v_add_f32_e32 v153, v179, v217
	v_add_f32_e32 v155, v127, v221
	v_mul_f32_e32 v149, 0xbfb8aa3b, v149
	v_mul_f32_e32 v151, 0xbfb8aa3b, v151
	v_mul_f32_e32 v153, 0xbfb8aa3b, v153
	v_mul_f32_e32 v155, 0xbfb8aa3b, v155
	v_exp_f32_e32 v149, v149
	v_exp_f32_e32 v151, v151
	v_exp_f32_e32 v153, v153
	v_exp_f32_e32 v155, v155
	v_add_f32_e32 v157, v128, v218
	v_add_f32_e32 v159, v124, v222
	v_add_f32_e32 v161, v129, v219
	v_add_f32_e32 v163, v125, v223
	v_mul_f32_e32 v157, 0xbfb8aa3b, v157
	v_mul_f32_e32 v159, 0xbfb8aa3b, v159
	v_mul_f32_e32 v161, 0xbfb8aa3b, v161
	v_mul_f32_e32 v163, 0xbfb8aa3b, v163
	v_exp_f32_e32 v157, v157
	v_exp_f32_e32 v159, v159
	v_exp_f32_e32 v161, v161
	v_exp_f32_e32 v163, v163
	v_add_f32_e32 v149, 1.0, v149
	v_add_f32_e32 v151, 1.0, v151
	v_add_f32_e32 v153, 1.0, v153
	v_add_f32_e32 v155, 1.0, v155
	v_rcp_f32_e32 v149, v149
	v_rcp_f32_e32 v151, v151
	v_rcp_f32_e32 v153, v153
	v_rcp_f32_e32 v155, v155
	v_add_f32_e32 v157, 1.0, v157
	v_add_f32_e32 v159, 1.0, v159
	v_add_f32_e32 v161, 1.0, v161
	v_add_f32_e32 v163, 1.0, v163
	v_rcp_f32_e32 v157, v157
	v_rcp_f32_e32 v159, v159
	v_rcp_f32_e32 v161, v161
	v_rcp_f32_e32 v163, v163
	v_cvt_pk_fp8_f32 v180, v149, v153
	v_cvt_pk_fp8_f32 v181, v151, v155
	v_lshl_add_u64 v[184:185], s[54:55], 0, v[0:1]
	v_lshl_add_u64 v[122:123], v[184:185], 0, v[122:123]
	v_cvt_pk_fp8_f32 v180, v157, v161 op_sel:[0, 0, 1]
	v_cvt_pk_fp8_f32 v181, v159, v163 op_sel:[0, 0, 1]
	global_store_dwordx2 v[122:123], v[180:181], off

; #define EGAS __attribute__((address_space(1)))
; __device__ __forceinline__ float sigm(float x) { return __builtin_amdgcn_rcpf(1.f + __expf(-x)); }
;     __device__ __forceinline__ void operator()(const f32x4 (&acc)[2][2][4][2], const Unit& u, int wr, int wc, int fr, int fq) const {
;     ...
;                     if constexpr (MODE == EP_IN) {
;                         if (pn < 12) {
;                             rope8(v0, v1, WSF(WS_ROPEA) + (row * 64 + (cw >> 1)) * 2);
;                             EGAS bf16_t* O = pn < 6 ? WSB(WS_QA) : WSB(WS_KA); const int c = (pn < 6 ? pn : pn - 6) * 256 + ct;
;                             st8(O + row * WA + c, v0, v1);
;                         } else if (pn < 18) { st8(WSB(WS_VA) + row * WA + (pn - 12) * 256 + ct, v0, v1);
;                         } else if (pn < 20) { st8(WSB(WS_QL) + row * QLORA + (pn - 18) * 256 + ct, v0, v1);
;                         } else if (pn < 22) { st8(WSB(WS_KVL) + row * KVLORA + (pn - 20) * 256 + ct, v0, v1);
;                         } else if (pn < 38) {
;                             const int gc = (pn - 22) * 256 + ct; const EGAS float* bg = (const EGAS float*)p.f0; const f32x4 b0 = *(const EGAS f32x4*)(bg + gc), b1 = *(const EGAS f32x4*)(bg + gc + 4);
; #pragma unroll
;                             for (int e = 0; e < 4; ++e) { v0[e] = sigm(v0[e] + b0[e]); v1[e] = sigm(v1[e] + b1[e]); }
;                             st8f8(WS8(WS_GATES) + row * 4096 + gc, v0, v1);
.LBB0_356:
	v_lshl_or_b32 v122, v150, 7, v138
	v_mov_b32_e32 v123, v1
	s_andn2_b64 vcc, exec, s[44:45]
	v_lshl_add_u64 v[180:181], v[122:123], 2, s[62:63]
	v_or_b32_e32 v122, s24, v138
	s_cbranch_vccnz .LBB0_358
	s_add_u32 s44, s8, s17
	s_addc_u32 s45, s9, 0
	v_ashrrev_i32_e32 v123, 31, v122
	v_pk_mul_f32 v[212:213], v[128:129], v[218:219]
	v_pk_mul_f32 v[128:129], v[128:129], v[218:219] op_sel:[1,0] op_sel_hi:[0,1]
	v_pk_mul_f32 v[214:215], v[178:179], v[216:217]
	v_pk_mul_f32 v[178:179], v[178:179], v[216:217] op_sel:[1,0] op_sel_hi:[0,1]
	v_add_f32_e32 v155, v128, v129
	v_pk_mul_f32 v[128:129], v[124:125], v[222:223]
	v_pk_mul_f32 v[124:125], v[124:125], v[222:223] op_sel:[1,0] op_sel_hi:[0,1]
	v_add_f32_e32 v151, v178, v179
	v_pk_mul_f32 v[178:179], v[126:127], v[220:221]
	v_pk_mul_f32 v[126:127], v[126:127], v[220:221] op_sel:[1,0] op_sel_hi:[0,1]
	v_add_f32_e32 v159, v124, v125
	v_lshl_add_u64 v[124:125], v[164:165], 1, s[44:45]
	v_add_f32_e32 v126, v126, v127
	v_sub_f32_e32 v127, v128, v129
	v_lshl_add_u64 v[128:129], v[122:123], 1, v[124:125]
	v_sub_f32_e32 v149, v214, v215
	v_sub_f32_e32 v153, v212, v213
	v_sub_f32_e32 v157, v178, v179
	v_cvt_pk_bf16_f32 v124, v149, v151
	v_cvt_pk_bf16_f32 v125, v153, v155
	v_cvt_pk_bf16_f32 v126, v157, v126
	v_cvt_pk_bf16_f32 v127, v127, v159
	global_store_dwordx4 v[128:129], v[124:127], off
.LBB0_358:
	v_cndmask_b32_e64 v123, 0, 1, s[42:43]
	v_mov_b32_e32 v177, v176
	v_mov_b32_e32 v124, v176
	v_mov_b32_e32 v125, v176
	v_cmp_ne_u32_e64 s[44:45], 1, v123
	v_cndmask_b32_e64 v123, 0, 1, s[36:37]
	v_pk_mul_f32 v[120:121], v[120:121], v[124:125]
	v_pk_mul_f32 v[118:119], v[118:119], v[176:177]
	v_pk_mul_f32 v[116:117], v[116:117], v[124:125]
	v_pk_mul_f32 v[114:115], v[114:115], v[176:177]
	s_mov_b64 s[86:87], -1
	s_andn2_b64 vcc, exec, s[42:43]
	v_cmp_ne_u32_e64 s[42:43], 1, v123
	s_cbranch_vccnz .LBB0_374
	s_and_b64 vcc, exec, s[42:43]
	s_mov_b64 s[36:37], -1
	s_cbranch_vccnz .LBB0_371
	s_andn2_b64 vcc, exec, s[30:31]
	s_cbranch_vccnz .LBB0_368
	s_andn2_b64 vcc, exec, s[28:29]
	s_cbranch_vccnz .LBB0_365
	s_andn2_b64 vcc, exec, s[26:27]
	s_cbranch_vccnz .LBB0_364
	v_or_b32_e32 v124, s19, v140
	v_mov_b32_e32 v125, v1
	v_mov_b32_e32 v128, v1
	v_mov_b32_e32 v129, v1
	v_add_f32_e32 v123, v118, v224
	v_add_f32_e32 v124, v114, v228
	v_add_f32_e32 v125, v119, v225
	v_add_f32_e32 v149, v115, v229
	v_mul_f32_e32 v123, 0xbfb8aa3b, v123
	v_mul_f32_e32 v124, 0xbfb8aa3b, v124
	v_mul_f32_e32 v125, 0xbfb8aa3b, v125
	v_mul_f32_e32 v149, 0xbfb8aa3b, v149
	v_exp_f32_e32 v123, v123
	v_exp_f32_e32 v124, v124
	v_exp_f32_e32 v125, v125
	v_exp_f32_e32 v149, v149
	v_add_f32_e32 v126, v120, v226
	v_add_f32_e32 v151, v116, v230
	v_add_f32_e32 v127, v121, v227
	v_add_f32_e32 v153, v117, v231
	v_mul_f32_e32 v126, 0xbfb8aa3b, v126
	v_mul_f32_e32 v151, 0xbfb8aa3b, v151
	v_mul_f32_e32 v127, 0xbfb8aa3b, v127
	v_mul_f32_e32 v153, 0xbfb8aa3b, v153
	v_exp_f32_e32 v126, v126
	v_exp_f32_e32 v151, v151
	v_exp_f32_e32 v127, v127
	v_exp_f32_e32 v153, v153
	v_add_f32_e32 v123, 1.0, v123
	v_add_f32_e32 v124, 1.0, v124
	v_add_f32_e32 v125, 1.0, v125
	v_add_f32_e32 v149, 1.0, v149
	v_rcp_f32_e32 v123, v123
	v_rcp_f32_e32 v124, v124
	v_rcp_f32_e32 v125, v125
	v_rcp_f32_e32 v149, v149
	v_add_f32_e32 v126, 1.0, v126
	v_add_f32_e32 v151, 1.0, v151
	v_add_f32_e32 v127, 1.0, v127
	v_add_f32_e32 v153, 1.0, v153
	v_rcp_f32_e32 v126, v126
	v_rcp_f32_e32 v151, v151
	v_rcp_f32_e32 v127, v127
	v_rcp_f32_e32 v153, v153
	v_cvt_pk_fp8_f32 v128, v123, v125
	v_cvt_pk_fp8_f32 v129, v124, v149
	v_lshl_add_u64 v[124:125], s[54:55], 0, v[0:1]
	v_add_u32_e32 v0, s19, v138
	v_cvt_pk_fp8_f32 v128, v126, v127 op_sel:[0, 0, 1]
	v_cvt_pk_fp8_f32 v129, v151, v153 op_sel:[0, 0, 1]
	v_lshl_add_u64 v[124:125], v[124:125], 0, v[0:1]
	global_store_dwordx2 v[124:125], v[128:129], off offset:128

; #define EGAS __attribute__((address_space(1)))
;     __device__ __forceinline__ void operator()(const f32x4 (&acc)[2][2][4][2], const Unit& u, int wr, int wc, int fr, int fq) const {
;     ...
;                     if constexpr (MODE == EP_IN) {
;                         if (pn < 12) {
;                             rope8(v0, v1, WSF(WS_ROPEA) + (row * 64 + (cw >> 1)) * 2);
;                             EGAS bf16_t* O = pn < 6 ? WSB(WS_QA) : WSB(WS_KA); const int c = (pn < 6 ? pn : pn - 6) * 256 + ct;
;                             st8(O + row * WA + c, v0, v1);
.LBB0_374:
	s_andn2_b64 vcc, exec, s[86:87]
	s_cbranch_vccnz .LBB0_376
	s_add_u32 s36, s8, s17
	s_addc_u32 s37, s9, 0
	s_ashr_i32 s25, s24, 31
	v_pk_mul_f32 v[178:179], v[118:119], v[216:217]
	v_pk_mul_f32 v[118:119], v[118:119], v[216:217] op_sel:[1,0] op_sel_hi:[0,1]
	v_pk_mul_f32 v[128:129], v[120:121], v[218:219]
	v_add_f32_e32 v123, v118, v119
	v_pk_mul_f32 v[118:119], v[120:121], v[218:219] op_sel:[1,0] op_sel_hi:[0,1]
	v_pk_mul_f32 v[120:121], v[114:115], v[220:221]
	v_pk_mul_f32 v[114:115], v[114:115], v[220:221] op_sel:[1,0] op_sel_hi:[0,1]
	v_sub_f32_e32 v120, v120, v121
	v_add_f32_e32 v121, v114, v115
	v_pk_mul_f32 v[114:115], v[116:117], v[222:223] op_sel:[1,0] op_sel_hi:[0,1]
	v_sub_f32_e32 v128, v128, v129
	v_add_f32_e32 v129, v118, v119
	v_pk_mul_f32 v[118:119], v[116:117], v[222:223]
	v_add_f32_e32 v125, v114, v115
	v_lshl_add_u64 v[114:115], v[164:165], 1, s[36:37]
	v_lshl_add_u64 v[116:117], s[24:25], 0, v[138:139]
	v_sub_f32_e32 v124, v118, v119
	v_lshl_add_u64 v[118:119], v[116:117], 1, v[114:115]
	v_sub_f32_e32 v0, v178, v179
	v_cvt_pk_bf16_f32 v114, v0, v123
	v_cvt_pk_bf16_f32 v115, v128, v129
	v_cvt_pk_bf16_f32 v116, v120, v121
	v_cvt_pk_bf16_f32 v117, v124, v125
	global_store_dwordx4 v[118:119], v[114:117], off offset:256
	v_add_u32_e32 v249, 0x10000, v248
	global_load_dwordx4 v[216:219], v249, s[62:63]
	global_load_dwordx4 v[220:223], v249, s[62:63] offset:16

; #define EGAS __attribute__((address_space(1)))
; __device__ __forceinline__ float sigm(float x) { return __builtin_amdgcn_rcpf(1.f + __expf(-x)); }
;     __device__ __forceinline__ void operator()(const f32x4 (&acc)[2][2][4][2], const Unit& u, int wr, int wc, int fr, int fq) const {
;     ...
;                         } else if (pn < 38) {
;                             const int gc = (pn - 22) * 256 + ct; const EGAS float* bg = (const EGAS float*)p.f0; const f32x4 b0 = *(const EGAS f32x4*)(bg + gc), b1 = *(const EGAS f32x4*)(bg + gc + 4);
; #pragma unroll
;                             for (int e = 0; e < 4; ++e) { v0[e] = sigm(v0[e] + b0[e]); v1[e] = sigm(v1[e] + b1[e]); }
;                             st8f8(WS8(WS_GATES) + row * 4096 + gc, v0, v1);
.LBB0_384:
	s_andn2_b64 vcc, exec, s[36:37]
	s_cbranch_vccnz .LBB0_386
	v_or_b32_e32 v120, s19, v138
	v_mov_b32_e32 v121, v1
	v_mov_b32_e32 v128, v1
	v_mov_b32_e32 v129, v1
	v_add_f32_e32 v119, v110, v216
	v_add_f32_e32 v123, v106, v220
	v_add_f32_e32 v124, v111, v217
	v_add_f32_e32 v125, v107, v221
	v_mul_f32_e32 v119, 0xbfb8aa3b, v119
	v_mul_f32_e32 v123, 0xbfb8aa3b, v123
	v_mul_f32_e32 v124, 0xbfb8aa3b, v124
	v_mul_f32_e32 v125, 0xbfb8aa3b, v125
	v_exp_f32_e32 v119, v119
	v_exp_f32_e32 v123, v123
	v_exp_f32_e32 v124, v124
	v_exp_f32_e32 v125, v125
	v_add_f32_e32 v126, v112, v218
	v_add_f32_e32 v149, v108, v222
	v_add_f32_e32 v127, v113, v219
	v_add_f32_e32 v151, v109, v223
	v_mul_f32_e32 v126, 0xbfb8aa3b, v126
	v_mul_f32_e32 v149, 0xbfb8aa3b, v149
	v_mul_f32_e32 v127, 0xbfb8aa3b, v127
	v_mul_f32_e32 v151, 0xbfb8aa3b, v151
	v_exp_f32_e32 v126, v126
	v_exp_f32_e32 v149, v149
	v_exp_f32_e32 v127, v127
	v_exp_f32_e32 v151, v151
	v_add_f32_e32 v119, 1.0, v119
	v_add_f32_e32 v123, 1.0, v123
	v_add_f32_e32 v124, 1.0, v124
	v_add_f32_e32 v125, 1.0, v125
	v_rcp_f32_e32 v119, v119
	v_rcp_f32_e32 v123, v123
	v_rcp_f32_e32 v124, v124
	v_rcp_f32_e32 v125, v125
	v_add_f32_e32 v126, 1.0, v126
	v_add_f32_e32 v149, 1.0, v149
	v_add_f32_e32 v127, 1.0, v127
	v_add_f32_e32 v151, 1.0, v151
	v_rcp_f32_e32 v126, v126
	v_rcp_f32_e32 v149, v149
	v_rcp_f32_e32 v127, v127
	v_rcp_f32_e32 v151, v151
	v_cvt_pk_fp8_f32 v128, v119, v124
	v_cvt_pk_fp8_f32 v129, v123, v125
	v_lshl_add_u64 v[124:125], s[54:55], 0, v[0:1]
	v_lshl_add_u64 v[120:121], v[124:125], 0, v[120:121]
	v_cvt_pk_fp8_f32 v128, v126, v127 op_sel:[0, 0, 1]
	v_cvt_pk_fp8_f32 v129, v149, v151 op_sel:[0, 0, 1]
	global_store_dwordx2 v[120:121], v[128:129], off

; #define EGAS __attribute__((address_space(1)))
; __device__ __forceinline__ float sigm(float x) { return __builtin_amdgcn_rcpf(1.f + __expf(-x)); }
;     __device__ __forceinline__ void operator()(const f32x4 (&acc)[2][2][4][2], const Unit& u, int wr, int wc, int fr, int fq) const {
;     ...
;                     if constexpr (MODE == EP_IN) {
;                         if (pn < 12) {
;                             rope8(v0, v1, WSF(WS_ROPEA) + (row * 64 + (cw >> 1)) * 2);
;                             EGAS bf16_t* O = pn < 6 ? WSB(WS_QA) : WSB(WS_KA); const int c = (pn < 6 ? pn : pn - 6) * 256 + ct;
;                             st8(O + row * WA + c, v0, v1);
;                         } else if (pn < 18) { st8(WSB(WS_VA) + row * WA + (pn - 12) * 256 + ct, v0, v1);
;                         } else if (pn < 20) { st8(WSB(WS_QL) + row * QLORA + (pn - 18) * 256 + ct, v0, v1);
;                         } else if (pn < 22) { st8(WSB(WS_KVL) + row * KVLORA + (pn - 20) * 256 + ct, v0, v1);
;                         } else if (pn < 38) {
;                             const int gc = (pn - 22) * 256 + ct; const EGAS float* bg = (const EGAS float*)p.f0; const f32x4 b0 = *(const EGAS f32x4*)(bg + gc), b1 = *(const EGAS f32x4*)(bg + gc + 4);
; #pragma unroll
;                             for (int e = 0; e < 4; ++e) { v0[e] = sigm(v0[e] + b0[e]); v1[e] = sigm(v1[e] + b1[e]); }
;                             st8f8(WS8(WS_GATES) + row * 4096 + gc, v0, v1);
.LBB0_396:
	v_lshl_or_b32 v118, v118, 7, v138
	v_mov_b32_e32 v119, v1
	s_andn2_b64 vcc, exec, s[36:37]
	v_lshl_add_u64 v[118:119], v[118:119], 2, s[62:63]
	s_cbranch_vccnz .LBB0_398
	s_add_u32 s36, s8, s17
	s_addc_u32 s37, s9, 0
	v_ashrrev_i32_e32 v123, 31, v122
	v_pk_mul_f32 v[128:129], v[110:111], v[224:225]
	v_pk_mul_f32 v[110:111], v[110:111], v[224:225] op_sel:[1,0] op_sel_hi:[0,1]
	v_pk_mul_f32 v[120:121], v[112:113], v[226:227]
	v_sub_f32_e32 v128, v128, v129
	v_add_f32_e32 v129, v110, v111
	v_pk_mul_f32 v[110:111], v[112:113], v[226:227] op_sel:[1,0] op_sel_hi:[0,1]
	v_pk_mul_f32 v[112:113], v[106:107], v[228:229]
	v_pk_mul_f32 v[106:107], v[106:107], v[228:229] op_sel:[1,0] op_sel_hi:[0,1]
	v_sub_f32_e32 v112, v112, v113
	v_add_f32_e32 v113, v106, v107
	v_pk_mul_f32 v[106:107], v[108:109], v[230:231] op_sel:[1,0] op_sel_hi:[0,1]
	v_sub_f32_e32 v120, v120, v121
	v_add_f32_e32 v121, v110, v111
	v_pk_mul_f32 v[110:111], v[108:109], v[230:231]
	v_add_f32_e32 v109, v106, v107
	v_lshl_add_u64 v[106:107], v[114:115], 1, s[36:37]
	v_sub_f32_e32 v124, v110, v111
	v_lshl_add_u64 v[110:111], v[122:123], 1, v[106:107]
	v_cvt_pk_bf16_f32 v106, v128, v129
	v_cvt_pk_bf16_f32 v107, v120, v121
	v_cvt_pk_bf16_f32 v108, v112, v113
	v_cvt_pk_bf16_f32 v109, v124, v109
	global_store_dwordx4 v[110:111], v[106:109], off
.LBB0_398:
	v_mov_b32_e32 v163, v162
	s_nop 0
	v_mov_b32_e32 v106, v162
	v_mov_b32_e32 v107, v162
	v_pk_mul_f32 v[104:105], v[104:105], v[106:107]
	v_pk_mul_f32 v[102:103], v[102:103], v[162:163]
	v_pk_mul_f32 v[100:101], v[100:101], v[106:107]
	v_pk_mul_f32 v[98:99], v[98:99], v[162:163]
	s_and_b64 vcc, exec, s[44:45]
	s_mov_b64 s[36:37], -1
	s_cbranch_vccnz .LBB0_414
	s_and_b64 vcc, exec, s[42:43]
	s_cbranch_vccnz .LBB0_411
	s_andn2_b64 vcc, exec, s[30:31]
	s_cbranch_vccnz .LBB0_408
	s_andn2_b64 vcc, exec, s[28:29]
	s_cbranch_vccnz .LBB0_405
	s_andn2_b64 vcc, exec, s[26:27]
	s_cbranch_vccnz .LBB0_404
	v_or_b32_e32 v106, s19, v140
	v_mov_b32_e32 v107, v1
	v_mov_b32_e32 v120, v1
	v_mov_b32_e32 v121, v1
	v_add_f32_e32 v106, v102, v224
	v_add_f32_e32 v110, v98, v228
	v_add_f32_e32 v107, v103, v225
	v_add_f32_e32 v111, v99, v229
	v_mul_f32_e32 v106, 0xbfb8aa3b, v106
	v_mul_f32_e32 v110, 0xbfb8aa3b, v110
	v_mul_f32_e32 v107, 0xbfb8aa3b, v107
	v_mul_f32_e32 v111, 0xbfb8aa3b, v111
	v_exp_f32_e32 v106, v106
	v_exp_f32_e32 v110, v110
	v_exp_f32_e32 v107, v107
	v_exp_f32_e32 v111, v111
	v_add_f32_e32 v108, v104, v226
	v_add_f32_e32 v112, v100, v230
	v_add_f32_e32 v109, v105, v227
	v_add_f32_e32 v113, v101, v231
	v_mul_f32_e32 v108, 0xbfb8aa3b, v108
	v_mul_f32_e32 v112, 0xbfb8aa3b, v112
	v_mul_f32_e32 v109, 0xbfb8aa3b, v109
	v_mul_f32_e32 v113, 0xbfb8aa3b, v113
	v_exp_f32_e32 v108, v108
	v_exp_f32_e32 v112, v112
	v_exp_f32_e32 v109, v109
	v_exp_f32_e32 v113, v113
	v_add_f32_e32 v106, 1.0, v106
	v_add_f32_e32 v110, 1.0, v110
	v_add_f32_e32 v107, 1.0, v107
	v_add_f32_e32 v111, 1.0, v111
	v_rcp_f32_e32 v106, v106
	v_rcp_f32_e32 v110, v110
	v_rcp_f32_e32 v107, v107
	v_rcp_f32_e32 v111, v111
	v_add_f32_e32 v108, 1.0, v108
	v_add_f32_e32 v112, 1.0, v112
	v_add_f32_e32 v109, 1.0, v109
	v_add_f32_e32 v113, 1.0, v113
	v_rcp_f32_e32 v108, v108
	v_rcp_f32_e32 v112, v112
	v_rcp_f32_e32 v109, v109
	v_rcp_f32_e32 v113, v113
	v_cvt_pk_fp8_f32 v120, v106, v107
	v_cvt_pk_fp8_f32 v121, v110, v111
	v_lshl_add_u64 v[106:107], s[54:55], 0, v[0:1]
	v_add_u32_e32 v0, s19, v138
	v_cvt_pk_fp8_f32 v120, v108, v109 op_sel:[0, 0, 1]
	v_cvt_pk_fp8_f32 v121, v112, v113 op_sel:[0, 0, 1]
	v_lshl_add_u64 v[106:107], v[106:107], 0, v[0:1]
	global_store_dwordx2 v[106:107], v[120:121], off offset:128

; #define EGAS __attribute__((address_space(1)))
;     __device__ __forceinline__ void operator()(const f32x4 (&acc)[2][2][4][2], const Unit& u, int wr, int wc, int fr, int fq) const {
;     ...
;                     if constexpr (MODE == EP_IN) {
;                         if (pn < 12) {
;                             rope8(v0, v1, WSF(WS_ROPEA) + (row * 64 + (cw >> 1)) * 2);
;                             EGAS bf16_t* O = pn < 6 ? WSB(WS_QA) : WSB(WS_KA); const int c = (pn < 6 ? pn : pn - 6) * 256 + ct;
;                             st8(O + row * WA + c, v0, v1);
.LBB0_414:
	s_andn2_b64 vcc, exec, s[36:37]
	s_cbranch_vccnz .LBB0_416
	s_add_u32 s36, s8, s17
	s_addc_u32 s37, s9, 0
	s_ashr_i32 s25, s24, 31
	v_pk_mul_f32 v[118:119], v[102:103], v[224:225]
	v_pk_mul_f32 v[102:103], v[102:103], v[224:225] op_sel:[1,0] op_sel_hi:[0,1]
	v_pk_mul_f32 v[116:117], v[104:105], v[226:227]
	v_add_f32_e32 v110, v102, v103
	v_pk_mul_f32 v[102:103], v[104:105], v[226:227] op_sel:[1,0] op_sel_hi:[0,1]
	v_pk_mul_f32 v[104:105], v[98:99], v[228:229]
	v_pk_mul_f32 v[98:99], v[98:99], v[228:229] op_sel:[1,0] op_sel_hi:[0,1]
	v_sub_f32_e32 v104, v104, v105
	v_add_f32_e32 v105, v98, v99
	v_pk_mul_f32 v[98:99], v[100:101], v[230:231] op_sel:[1,0] op_sel_hi:[0,1]
	v_add_f32_e32 v112, v102, v103
	v_pk_mul_f32 v[102:103], v[100:101], v[230:231]
	v_add_f32_e32 v107, v98, v99
	v_lshl_add_u64 v[98:99], v[114:115], 1, s[36:37]
	v_lshl_add_u64 v[100:101], s[24:25], 0, v[138:139]
	v_sub_f32_e32 v106, v102, v103
	v_lshl_add_u64 v[102:103], v[100:101], 1, v[98:99]
	v_sub_f32_e32 v0, v118, v119
	v_sub_f32_e32 v111, v116, v117
	v_cvt_pk_bf16_f32 v98, v0, v110
	v_cvt_pk_bf16_f32 v99, v111, v112
	v_cvt_pk_bf16_f32 v100, v104, v105
	v_cvt_pk_bf16_f32 v101, v106, v107
	global_store_dwordx4 v[102:103], v[98:101], off offset:256
	v_add_u32_e32 v249, 0x12000, v248
	global_load_dwordx4 v[224:227], v249, s[62:63]
	global_load_dwordx4 v[228:231], v249, s[62:63] offset:16

; #define EGAS __attribute__((address_space(1)))
; __device__ __forceinline__ float sigm(float x) { return __builtin_amdgcn_rcpf(1.f + __expf(-x)); }
;     __device__ __forceinline__ void operator()(const f32x4 (&acc)[2][2][4][2], const Unit& u, int wr, int wc, int fr, int fq) const {
;     ...
;                         } else if (pn < 38) {
;                             const int gc = (pn - 22) * 256 + ct; const EGAS float* bg = (const EGAS float*)p.f0; const f32x4 b0 = *(const EGAS f32x4*)(bg + gc), b1 = *(const EGAS f32x4*)(bg + gc + 4);
; #pragma unroll
;                             for (int e = 0; e < 4; ++e) { v0[e] = sigm(v0[e] + b0[e]); v1[e] = sigm(v1[e] + b1[e]); }
;                             st8f8(WS8(WS_GATES) + row * 4096 + gc, v0, v1);
.LBB0_424:
	s_andn2_b64 vcc, exec, s[36:37]
	s_cbranch_vccnz .LBB0_426
	v_or_b32_e32 v112, s19, v138
	v_mov_b32_e32 v113, v1
	v_mov_b32_e32 v114, v1
	v_mov_b32_e32 v115, v1
	v_add_f32_e32 v103, v94, v216
	v_add_f32_e32 v104, v90, v220
	v_add_f32_e32 v105, v95, v217
	v_add_f32_e32 v108, v91, v221
	v_mul_f32_e32 v103, 0xbfb8aa3b, v103
	v_mul_f32_e32 v104, 0xbfb8aa3b, v104
	v_mul_f32_e32 v105, 0xbfb8aa3b, v105
	v_mul_f32_e32 v108, 0xbfb8aa3b, v108
	v_exp_f32_e32 v103, v103
	v_exp_f32_e32 v104, v104
	v_exp_f32_e32 v105, v105
	v_exp_f32_e32 v108, v108
	v_add_f32_e32 v106, v96, v218
	v_add_f32_e32 v109, v92, v222
	v_add_f32_e32 v107, v97, v219
	v_add_f32_e32 v110, v93, v223
	v_mul_f32_e32 v106, 0xbfb8aa3b, v106
	v_mul_f32_e32 v109, 0xbfb8aa3b, v109
	v_mul_f32_e32 v107, 0xbfb8aa3b, v107
	v_mul_f32_e32 v110, 0xbfb8aa3b, v110
	v_exp_f32_e32 v106, v106
	v_exp_f32_e32 v109, v109
	v_exp_f32_e32 v107, v107
	v_exp_f32_e32 v110, v110
	v_add_f32_e32 v103, 1.0, v103
	v_add_f32_e32 v104, 1.0, v104
	v_add_f32_e32 v105, 1.0, v105
	v_add_f32_e32 v108, 1.0, v108
	v_rcp_f32_e32 v103, v103
	v_rcp_f32_e32 v104, v104
	v_rcp_f32_e32 v105, v105
	v_rcp_f32_e32 v108, v108
	v_add_f32_e32 v106, 1.0, v106
	v_add_f32_e32 v109, 1.0, v109
	v_add_f32_e32 v107, 1.0, v107
	v_add_f32_e32 v110, 1.0, v110
	v_rcp_f32_e32 v106, v106
	v_rcp_f32_e32 v109, v109
	v_rcp_f32_e32 v107, v107
	v_rcp_f32_e32 v110, v110
	v_cvt_pk_fp8_f32 v114, v103, v105
	v_cvt_pk_fp8_f32 v115, v104, v108
	v_lshl_add_u64 v[104:105], s[54:55], 0, v[0:1]
	v_lshl_add_u64 v[104:105], v[104:105], 0, v[112:113]
	v_cvt_pk_fp8_f32 v114, v106, v107 op_sel:[0, 0, 1]
	v_cvt_pk_fp8_f32 v115, v109, v110 op_sel:[0, 0, 1]
	global_store_dwordx2 v[104:105], v[114:115], off

; #define EGAS __attribute__((address_space(1)))
; __device__ __forceinline__ float sigm(float x) { return __builtin_amdgcn_rcpf(1.f + __expf(-x)); }
;     __device__ __forceinline__ void operator()(const f32x4 (&acc)[2][2][4][2], const Unit& u, int wr, int wc, int fr, int fq) const {
;     ...
;                     if constexpr (MODE == EP_IN) {
;                         if (pn < 12) {
;                             rope8(v0, v1, WSF(WS_ROPEA) + (row * 64 + (cw >> 1)) * 2);
;                             EGAS bf16_t* O = pn < 6 ? WSB(WS_QA) : WSB(WS_KA); const int c = (pn < 6 ? pn : pn - 6) * 256 + ct;
;                             st8(O + row * WA + c, v0, v1);
;                         } else if (pn < 18) { st8(WSB(WS_VA) + row * WA + (pn - 12) * 256 + ct, v0, v1);
;                         } else if (pn < 20) { st8(WSB(WS_QL) + row * QLORA + (pn - 18) * 256 + ct, v0, v1);
;                         } else if (pn < 22) { st8(WSB(WS_KVL) + row * KVLORA + (pn - 20) * 256 + ct, v0, v1);
;                         } else if (pn < 38) {
;                             const int gc = (pn - 22) * 256 + ct; const EGAS float* bg = (const EGAS float*)p.f0; const f32x4 b0 = *(const EGAS f32x4*)(bg + gc), b1 = *(const EGAS f32x4*)(bg + gc + 4);
; #pragma unroll
;                             for (int e = 0; e < 4; ++e) { v0[e] = sigm(v0[e] + b0[e]); v1[e] = sigm(v1[e] + b1[e]); }
;                             st8f8(WS8(WS_GATES) + row * 4096 + gc, v0, v1);
.LBB0_436:
	v_lshl_or_b32 v102, v102, 7, v138
	v_mov_b32_e32 v103, v1
	s_andn2_b64 vcc, exec, s[36:37]
	v_lshl_add_u64 v[102:103], v[102:103], 2, s[62:63]
	s_cbranch_vccnz .LBB0_438
	s_add_u32 s36, s8, s17
	s_addc_u32 s37, s9, 0
	v_ashrrev_i32_e32 v123, 31, v122
	v_pk_mul_f32 v[114:115], v[94:95], v[232:233]
	v_pk_mul_f32 v[94:95], v[94:95], v[232:233] op_sel:[1,0] op_sel_hi:[0,1]
	v_pk_mul_f32 v[112:113], v[96:97], v[234:235]
	v_add_f32_e32 v108, v94, v95
	v_pk_mul_f32 v[94:95], v[96:97], v[234:235] op_sel:[1,0] op_sel_hi:[0,1]
	v_pk_mul_f32 v[96:97], v[90:91], v[236:237]
	v_pk_mul_f32 v[90:91], v[90:91], v[236:237] op_sel:[1,0] op_sel_hi:[0,1]
	v_sub_f32_e32 v96, v96, v97
	v_add_f32_e32 v97, v90, v91
	v_pk_mul_f32 v[90:91], v[92:93], v[238:239] op_sel:[1,0] op_sel_hi:[0,1]
	v_add_f32_e32 v110, v94, v95
	v_pk_mul_f32 v[94:95], v[92:93], v[238:239]
	v_add_f32_e32 v93, v90, v91
	v_lshl_add_u64 v[90:91], v[98:99], 1, s[36:37]
	v_sub_f32_e32 v104, v94, v95
	v_lshl_add_u64 v[94:95], v[122:123], 1, v[90:91]
	v_sub_f32_e32 v114, v114, v115
	v_sub_f32_e32 v109, v112, v113
	v_cvt_pk_bf16_f32 v90, v114, v108
	v_cvt_pk_bf16_f32 v91, v109, v110
	v_cvt_pk_bf16_f32 v92, v96, v97
	v_cvt_pk_bf16_f32 v93, v104, v93
	global_store_dwordx4 v[94:95], v[90:93], off
.LBB0_438:
	v_mov_b32_e32 v161, v160
	s_nop 0
	v_mov_b32_e32 v90, v160
	v_mov_b32_e32 v91, v160
	v_pk_mul_f32 v[88:89], v[88:89], v[90:91]
	v_pk_mul_f32 v[86:87], v[86:87], v[160:161]
	v_pk_mul_f32 v[84:85], v[84:85], v[90:91]
	v_pk_mul_f32 v[82:83], v[82:83], v[160:161]
	s_and_b64 vcc, exec, s[44:45]
	s_mov_b64 s[36:37], -1
	s_cbranch_vccnz .LBB0_454
	s_and_b64 vcc, exec, s[42:43]
	s_cbranch_vccnz .LBB0_451
	s_andn2_b64 vcc, exec, s[30:31]
	s_cbranch_vccnz .LBB0_448
	s_andn2_b64 vcc, exec, s[28:29]
	s_cbranch_vccnz .LBB0_445
	s_andn2_b64 vcc, exec, s[26:27]
	s_cbranch_vccnz .LBB0_444
	v_or_b32_e32 v90, s19, v140
	v_mov_b32_e32 v91, v1
	v_mov_b32_e32 v104, v1
	v_mov_b32_e32 v105, v1
	v_add_f32_e32 v90, v86, v224
	v_add_f32_e32 v94, v82, v228
	v_add_f32_e32 v91, v87, v225
	v_add_f32_e32 v95, v83, v229
	v_mul_f32_e32 v90, 0xbfb8aa3b, v90
	v_mul_f32_e32 v94, 0xbfb8aa3b, v94
	v_mul_f32_e32 v91, 0xbfb8aa3b, v91
	v_mul_f32_e32 v95, 0xbfb8aa3b, v95
	v_exp_f32_e32 v90, v90
	v_exp_f32_e32 v94, v94
	v_exp_f32_e32 v91, v91
	v_exp_f32_e32 v95, v95
	v_add_f32_e32 v92, v88, v226
	v_add_f32_e32 v96, v84, v230
	v_add_f32_e32 v93, v89, v227
	v_add_f32_e32 v97, v85, v231
	v_mul_f32_e32 v92, 0xbfb8aa3b, v92
	v_mul_f32_e32 v96, 0xbfb8aa3b, v96
	v_mul_f32_e32 v93, 0xbfb8aa3b, v93
	v_mul_f32_e32 v97, 0xbfb8aa3b, v97
	v_exp_f32_e32 v92, v92
	v_exp_f32_e32 v96, v96
	v_exp_f32_e32 v93, v93
	v_exp_f32_e32 v97, v97
	v_add_f32_e32 v90, 1.0, v90
	v_add_f32_e32 v94, 1.0, v94
	v_add_f32_e32 v91, 1.0, v91
	v_add_f32_e32 v95, 1.0, v95
	v_rcp_f32_e32 v90, v90
	v_rcp_f32_e32 v94, v94
	v_rcp_f32_e32 v91, v91
	v_rcp_f32_e32 v95, v95
	v_add_f32_e32 v92, 1.0, v92
	v_add_f32_e32 v96, 1.0, v96
	v_add_f32_e32 v93, 1.0, v93
	v_add_f32_e32 v97, 1.0, v97
	v_rcp_f32_e32 v92, v92
	v_rcp_f32_e32 v96, v96
	v_rcp_f32_e32 v93, v93
	v_rcp_f32_e32 v97, v97
	v_cvt_pk_fp8_f32 v104, v90, v91
	v_cvt_pk_fp8_f32 v105, v94, v95
	v_lshl_add_u64 v[90:91], s[54:55], 0, v[0:1]
	v_cvt_pk_fp8_f32 v104, v92, v93 op_sel:[0, 0, 1]
	v_cvt_pk_fp8_f32 v105, v96, v97 op_sel:[0, 0, 1]
	v_add_u32_e32 v92, s19, v138
	v_mov_b32_e32 v93, v1
	v_lshl_add_u64 v[90:91], v[90:91], 0, v[92:93]
	global_store_dwordx2 v[90:91], v[104:105], off offset:128

; #define EGAS __attribute__((address_space(1)))
;     __device__ __forceinline__ void operator()(const f32x4 (&acc)[2][2][4][2], const Unit& u, int wr, int wc, int fr, int fq) const {
;     ...
;                         if (pn < 12) {
;                             rope8(v0, v1, WSF(WS_ROPEA) + (row * 64 + (cw >> 1)) * 2);
;                             EGAS bf16_t* O = pn < 6 ? WSB(WS_QA) : WSB(WS_KA); const int c = (pn < 6 ? pn : pn - 6) * 256 + ct;
;                             st8(O + row * WA + c, v0, v1);
.LBB0_454:
	s_andn2_b64 vcc, exec, s[36:37]
	s_cbranch_vccnz .LBB0_456
	s_add_u32 s36, s8, s17
	s_addc_u32 s37, s9, 0
	s_ashr_i32 s25, s24, 31
	v_pk_mul_f32 v[102:103], v[86:87], v[232:233]
	v_pk_mul_f32 v[86:87], v[86:87], v[232:233] op_sel:[1,0] op_sel_hi:[0,1]
	v_pk_mul_f32 v[100:101], v[88:89], v[234:235]
	v_add_f32_e32 v94, v86, v87
	v_pk_mul_f32 v[86:87], v[88:89], v[234:235] op_sel:[1,0] op_sel_hi:[0,1]
	v_pk_mul_f32 v[88:89], v[82:83], v[236:237]
	v_pk_mul_f32 v[82:83], v[82:83], v[236:237] op_sel:[1,0] op_sel_hi:[0,1]
	v_sub_f32_e32 v88, v88, v89
	v_add_f32_e32 v89, v82, v83
	v_pk_mul_f32 v[82:83], v[84:85], v[238:239] op_sel:[1,0] op_sel_hi:[0,1]
	v_add_f32_e32 v96, v86, v87
	v_pk_mul_f32 v[86:87], v[84:85], v[238:239]
	v_add_f32_e32 v91, v82, v83
	v_lshl_add_u64 v[82:83], v[98:99], 1, s[36:37]
	v_lshl_add_u64 v[84:85], s[24:25], 0, v[138:139]
	v_sub_f32_e32 v90, v86, v87
	v_lshl_add_u64 v[86:87], v[84:85], 1, v[82:83]
	v_sub_f32_e32 v0, v102, v103
	v_sub_f32_e32 v95, v100, v101
	v_cvt_pk_bf16_f32 v82, v0, v94
	v_cvt_pk_bf16_f32 v83, v95, v96
	v_cvt_pk_bf16_f32 v84, v88, v89
	v_cvt_pk_bf16_f32 v85, v90, v91
	global_store_dwordx4 v[86:87], v[82:85], off offset:256
	v_add_u32_e32 v249, 0x14000, v248
	global_load_dwordx4 v[232:235], v249, s[62:63]
	global_load_dwordx4 v[236:239], v249, s[62:63] offset:16

; #define EGAS __attribute__((address_space(1)))
; __device__ __forceinline__ float sigm(float x) { return __builtin_amdgcn_rcpf(1.f + __expf(-x)); }
; __device__ __forceinline__ void st8f8(EGAS unsigned char* dst, f32x4 v0, f32x4 v1) {
;     int w0 = __builtin_amdgcn_cvt_pk_fp8_f32(v0[0], v0[1], 0, false); w0 = __builtin_amdgcn_cvt_pk_fp8_f32(v0[2], v0[3], w0, true);
;     int w1 = __builtin_amdgcn_cvt_pk_fp8_f32(v1[0], v1[1], 0, false); w1 = __builtin_amdgcn_cvt_pk_fp8_f32(v1[2], v1[3], w1, true);
;     *(EGAS u32x2e*)dst = (u32x2e){(unsigned)w0, (unsigned)w1}; }
;     __device__ __forceinline__ void operator()(const f32x4 (&acc)[2][2][4][2], const Unit& u, int wr, int wc, int fr, int fq) const {
;     ...
;                         } else if (pn < 38) {
;                             const int gc = (pn - 22) * 256 + ct; const EGAS float* bg = (const EGAS float*)p.f0; const f32x4 b0 = *(const EGAS f32x4*)(bg + gc), b1 = *(const EGAS f32x4*)(bg + gc + 4);
; #pragma unroll
;                             for (int e = 0; e < 4; ++e) { v0[e] = sigm(v0[e] + b0[e]); v1[e] = sigm(v1[e] + b1[e]); }
;                             st8f8(WS8(WS_GATES) + row * 4096 + gc, v0, v1);
.LBB0_464:
	s_andn2_b64 vcc, exec, s[36:37]
	s_cbranch_vccnz .LBB0_466
	v_or_b32_e32 v96, s19, v138
	v_mov_b32_e32 v97, v1
	v_mov_b32_e32 v98, v1
	v_mov_b32_e32 v99, v1
	v_add_f32_e32 v87, v78, v216
	v_add_f32_e32 v88, v74, v220
	v_add_f32_e32 v89, v79, v217
	v_add_f32_e32 v92, v75, v221
	v_mul_f32_e32 v87, 0xbfb8aa3b, v87
	v_mul_f32_e32 v88, 0xbfb8aa3b, v88
	v_mul_f32_e32 v89, 0xbfb8aa3b, v89
	v_mul_f32_e32 v92, 0xbfb8aa3b, v92
	v_exp_f32_e32 v87, v87
	v_exp_f32_e32 v88, v88
	v_exp_f32_e32 v89, v89
	v_exp_f32_e32 v92, v92
	v_add_f32_e32 v90, v80, v218
	v_add_f32_e32 v93, v76, v222
	v_add_f32_e32 v91, v81, v219
	v_add_f32_e32 v94, v77, v223
	v_mul_f32_e32 v90, 0xbfb8aa3b, v90
	v_mul_f32_e32 v93, 0xbfb8aa3b, v93
	v_mul_f32_e32 v91, 0xbfb8aa3b, v91
	v_mul_f32_e32 v94, 0xbfb8aa3b, v94
	v_exp_f32_e32 v90, v90
	v_exp_f32_e32 v93, v93
	v_exp_f32_e32 v91, v91
	v_exp_f32_e32 v94, v94
	v_add_f32_e32 v87, 1.0, v87
	v_add_f32_e32 v88, 1.0, v88
	v_add_f32_e32 v89, 1.0, v89
	v_add_f32_e32 v92, 1.0, v92
	v_rcp_f32_e32 v87, v87
	v_rcp_f32_e32 v88, v88
	v_rcp_f32_e32 v89, v89
	v_rcp_f32_e32 v92, v92
	v_add_f32_e32 v90, 1.0, v90
	v_add_f32_e32 v93, 1.0, v93
	v_add_f32_e32 v91, 1.0, v91
	v_add_f32_e32 v94, 1.0, v94
	v_rcp_f32_e32 v90, v90
	v_rcp_f32_e32 v93, v93
	v_rcp_f32_e32 v91, v91
	v_rcp_f32_e32 v94, v94
	v_cvt_pk_fp8_f32 v98, v87, v89
	v_cvt_pk_fp8_f32 v99, v88, v92
	v_lshl_add_u64 v[88:89], s[54:55], 0, v[0:1]
	v_lshl_add_u64 v[88:89], v[88:89], 0, v[96:97]
	v_cvt_pk_fp8_f32 v98, v90, v91 op_sel:[0, 0, 1]
	v_cvt_pk_fp8_f32 v99, v93, v94 op_sel:[0, 0, 1]
	global_store_dwordx2 v[88:89], v[98:99], off

; #define EGAS __attribute__((address_space(1)))
; __device__ __forceinline__ float sigm(float x) { return __builtin_amdgcn_rcpf(1.f + __expf(-x)); }
;     __device__ __forceinline__ void operator()(const f32x4 (&acc)[2][2][4][2], const Unit& u, int wr, int wc, int fr, int fq) const {
;     ...
;                     if constexpr (MODE == EP_IN) {
;                         if (pn < 12) {
;                             rope8(v0, v1, WSF(WS_ROPEA) + (row * 64 + (cw >> 1)) * 2);
;                             EGAS bf16_t* O = pn < 6 ? WSB(WS_QA) : WSB(WS_KA); const int c = (pn < 6 ? pn : pn - 6) * 256 + ct;
;                             st8(O + row * WA + c, v0, v1);
;                         } else if (pn < 18) { st8(WSB(WS_VA) + row * WA + (pn - 12) * 256 + ct, v0, v1);
;                         } else if (pn < 20) { st8(WSB(WS_QL) + row * QLORA + (pn - 18) * 256 + ct, v0, v1);
;                         } else if (pn < 22) { st8(WSB(WS_KVL) + row * KVLORA + (pn - 20) * 256 + ct, v0, v1);
;                         } else if (pn < 38) {
;                             const int gc = (pn - 22) * 256 + ct; const EGAS float* bg = (const EGAS float*)p.f0; const f32x4 b0 = *(const EGAS f32x4*)(bg + gc), b1 = *(const EGAS f32x4*)(bg + gc + 4);
; #pragma unroll
;                             for (int e = 0; e < 4; ++e) { v0[e] = sigm(v0[e] + b0[e]); v1[e] = sigm(v1[e] + b1[e]); }
;                             st8f8(WS8(WS_GATES) + row * 4096 + gc, v0, v1);
.LBB0_476:
	v_lshl_or_b32 v86, v86, 7, v138
	v_mov_b32_e32 v87, v1
	s_andn2_b64 vcc, exec, s[36:37]
	v_lshl_add_u64 v[86:87], v[86:87], 2, s[62:63]
	s_cbranch_vccnz .LBB0_478
	s_add_u32 s36, s8, s17
	s_addc_u32 s37, s9, 0
	v_ashrrev_i32_e32 v123, 31, v122
	v_pk_mul_f32 v[98:99], v[78:79], v[240:241]
	v_pk_mul_f32 v[78:79], v[78:79], v[240:241] op_sel:[1,0] op_sel_hi:[0,1]
	v_pk_mul_f32 v[96:97], v[80:81], v[242:243]
	v_add_f32_e32 v92, v78, v79
	v_pk_mul_f32 v[78:79], v[80:81], v[242:243] op_sel:[1,0] op_sel_hi:[0,1]
	v_pk_mul_f32 v[80:81], v[74:75], v[244:245]
	v_pk_mul_f32 v[74:75], v[74:75], v[244:245] op_sel:[1,0] op_sel_hi:[0,1]
	v_sub_f32_e32 v80, v80, v81
	v_add_f32_e32 v81, v74, v75
	v_pk_mul_f32 v[74:75], v[76:77], v[246:247] op_sel:[1,0] op_sel_hi:[0,1]
	v_add_f32_e32 v94, v78, v79
	v_pk_mul_f32 v[78:79], v[76:77], v[246:247]
	v_add_f32_e32 v77, v74, v75
	v_lshl_add_u64 v[74:75], v[82:83], 1, s[36:37]
	v_sub_f32_e32 v88, v78, v79
	v_lshl_add_u64 v[78:79], v[122:123], 1, v[74:75]
	v_sub_f32_e32 v98, v98, v99
	v_sub_f32_e32 v93, v96, v97
	v_cvt_pk_bf16_f32 v74, v98, v92
	v_cvt_pk_bf16_f32 v75, v93, v94
	v_cvt_pk_bf16_f32 v76, v80, v81
	v_cvt_pk_bf16_f32 v77, v88, v77
	global_store_dwordx4 v[78:79], v[74:77], off
.LBB0_478:
	v_mov_b32_e32 v159, v158
	s_nop 0
	v_mov_b32_e32 v74, v158
	v_mov_b32_e32 v75, v158
	v_pk_mul_f32 v[72:73], v[72:73], v[74:75]
	v_pk_mul_f32 v[70:71], v[70:71], v[158:159]
	v_pk_mul_f32 v[68:69], v[68:69], v[74:75]
	v_pk_mul_f32 v[66:67], v[66:67], v[158:159]
	s_and_b64 vcc, exec, s[44:45]
	s_mov_b64 s[36:37], -1
	s_cbranch_vccnz .LBB0_494
	s_and_b64 vcc, exec, s[42:43]
	s_cbranch_vccnz .LBB0_491
	s_andn2_b64 vcc, exec, s[30:31]
	s_cbranch_vccnz .LBB0_488
	s_andn2_b64 vcc, exec, s[28:29]
	s_cbranch_vccnz .LBB0_485
	s_andn2_b64 vcc, exec, s[26:27]
	s_cbranch_vccnz .LBB0_484
	v_or_b32_e32 v74, s19, v140
	v_mov_b32_e32 v75, v1
	v_mov_b32_e32 v88, v1
	v_mov_b32_e32 v89, v1
	v_add_f32_e32 v74, v70, v224
	v_add_f32_e32 v78, v66, v228
	v_add_f32_e32 v75, v71, v225
	v_add_f32_e32 v79, v67, v229
	v_mul_f32_e32 v74, 0xbfb8aa3b, v74
	v_mul_f32_e32 v78, 0xbfb8aa3b, v78
	v_mul_f32_e32 v75, 0xbfb8aa3b, v75
	v_mul_f32_e32 v79, 0xbfb8aa3b, v79
	v_exp_f32_e32 v74, v74
	v_exp_f32_e32 v78, v78
	v_exp_f32_e32 v75, v75
	v_exp_f32_e32 v79, v79
	v_add_f32_e32 v76, v72, v226
	v_add_f32_e32 v80, v68, v230
	v_add_f32_e32 v77, v73, v227
	v_add_f32_e32 v81, v69, v231
	v_mul_f32_e32 v76, 0xbfb8aa3b, v76
	v_mul_f32_e32 v80, 0xbfb8aa3b, v80
	v_mul_f32_e32 v77, 0xbfb8aa3b, v77
	v_mul_f32_e32 v81, 0xbfb8aa3b, v81
	v_exp_f32_e32 v76, v76
	v_exp_f32_e32 v80, v80
	v_exp_f32_e32 v77, v77
	v_exp_f32_e32 v81, v81
	v_add_f32_e32 v74, 1.0, v74
	v_add_f32_e32 v78, 1.0, v78
	v_add_f32_e32 v75, 1.0, v75
	v_add_f32_e32 v79, 1.0, v79
	v_rcp_f32_e32 v74, v74
	v_rcp_f32_e32 v78, v78
	v_rcp_f32_e32 v75, v75
	v_rcp_f32_e32 v79, v79
	v_add_f32_e32 v76, 1.0, v76
	v_add_f32_e32 v80, 1.0, v80
	v_add_f32_e32 v77, 1.0, v77
	v_add_f32_e32 v81, 1.0, v81
	v_rcp_f32_e32 v76, v76
	v_rcp_f32_e32 v80, v80
	v_rcp_f32_e32 v77, v77
	v_rcp_f32_e32 v81, v81
	v_cvt_pk_fp8_f32 v88, v74, v75
	v_cvt_pk_fp8_f32 v89, v78, v79
	v_lshl_add_u64 v[74:75], s[54:55], 0, v[0:1]
	v_cvt_pk_fp8_f32 v88, v76, v77 op_sel:[0, 0, 1]
	v_cvt_pk_fp8_f32 v89, v80, v81 op_sel:[0, 0, 1]
	v_add_u32_e32 v76, s19, v138
	v_mov_b32_e32 v77, v1
	v_lshl_add_u64 v[74:75], v[74:75], 0, v[76:77]
	global_store_dwordx2 v[74:75], v[88:89], off offset:128

; #define EGAS __attribute__((address_space(1)))
;     __device__ __forceinline__ void operator()(const f32x4 (&acc)[2][2][4][2], const Unit& u, int wr, int wc, int fr, int fq) const {
;     ...
;                         if (pn < 12) {
;                             rope8(v0, v1, WSF(WS_ROPEA) + (row * 64 + (cw >> 1)) * 2);
;                             EGAS bf16_t* O = pn < 6 ? WSB(WS_QA) : WSB(WS_KA); const int c = (pn < 6 ? pn : pn - 6) * 256 + ct;
;                             st8(O + row * WA + c, v0, v1);
.LBB0_494:
	s_andn2_b64 vcc, exec, s[36:37]
	s_cbranch_vccnz .LBB0_496
	s_add_u32 s36, s8, s17
	s_addc_u32 s37, s9, 0
	s_ashr_i32 s25, s24, 31
	v_pk_mul_f32 v[86:87], v[70:71], v[240:241]
	v_pk_mul_f32 v[70:71], v[70:71], v[240:241] op_sel:[1,0] op_sel_hi:[0,1]
	v_pk_mul_f32 v[84:85], v[72:73], v[242:243]
	v_add_f32_e32 v78, v70, v71
	v_pk_mul_f32 v[70:71], v[72:73], v[242:243] op_sel:[1,0] op_sel_hi:[0,1]
	v_pk_mul_f32 v[72:73], v[66:67], v[244:245]
	v_pk_mul_f32 v[66:67], v[66:67], v[244:245] op_sel:[1,0] op_sel_hi:[0,1]
	v_sub_f32_e32 v72, v72, v73
	v_add_f32_e32 v73, v66, v67
	v_pk_mul_f32 v[66:67], v[68:69], v[246:247] op_sel:[1,0] op_sel_hi:[0,1]
	v_add_f32_e32 v80, v70, v71
	v_pk_mul_f32 v[70:71], v[68:69], v[246:247]
	v_add_f32_e32 v75, v66, v67
	v_lshl_add_u64 v[66:67], v[82:83], 1, s[36:37]
	v_lshl_add_u64 v[68:69], s[24:25], 0, v[138:139]
	v_sub_f32_e32 v74, v70, v71
	v_lshl_add_u64 v[70:71], v[68:69], 1, v[66:67]
	v_sub_f32_e32 v0, v86, v87
	v_sub_f32_e32 v79, v84, v85
	v_cvt_pk_bf16_f32 v66, v0, v78
	v_cvt_pk_bf16_f32 v67, v79, v80
	v_cvt_pk_bf16_f32 v68, v72, v73
	v_cvt_pk_bf16_f32 v69, v74, v75
	global_store_dwordx4 v[70:71], v[66:69], off offset:256
	v_add_u32_e32 v249, 0x16000, v248
	global_load_dwordx4 v[240:243], v249, s[62:63]
	global_load_dwordx4 v[244:247], v249, s[62:63] offset:16

; #define EGAS __attribute__((address_space(1)))
; __device__ __forceinline__ float sigm(float x) { return __builtin_amdgcn_rcpf(1.f + __expf(-x)); }
; __device__ __forceinline__ void st8f8(EGAS unsigned char* dst, f32x4 v0, f32x4 v1) {
;     int w0 = __builtin_amdgcn_cvt_pk_fp8_f32(v0[0], v0[1], 0, false); w0 = __builtin_amdgcn_cvt_pk_fp8_f32(v0[2], v0[3], w0, true);
;     int w1 = __builtin_amdgcn_cvt_pk_fp8_f32(v1[0], v1[1], 0, false); w1 = __builtin_amdgcn_cvt_pk_fp8_f32(v1[2], v1[3], w1, true);
;     *(EGAS u32x2e*)dst = (u32x2e){(unsigned)w0, (unsigned)w1}; }
;     __device__ __forceinline__ void operator()(const f32x4 (&acc)[2][2][4][2], const Unit& u, int wr, int wc, int fr, int fq) const {
;     ...
;                         } else if (pn < 38) {
;                             const int gc = (pn - 22) * 256 + ct; const EGAS float* bg = (const EGAS float*)p.f0; const f32x4 b0 = *(const EGAS f32x4*)(bg + gc), b1 = *(const EGAS f32x4*)(bg + gc + 4);
; #pragma unroll
;                             for (int e = 0; e < 4; ++e) { v0[e] = sigm(v0[e] + b0[e]); v1[e] = sigm(v1[e] + b1[e]); }
;                             st8f8(WS8(WS_GATES) + row * 4096 + gc, v0, v1);
.LBB0_504:
	s_andn2_b64 vcc, exec, s[36:37]
	s_cbranch_vccnz .LBB0_506
	v_or_b32_e32 v80, s19, v138
	v_mov_b32_e32 v81, v1
	v_mov_b32_e32 v82, v1
	v_mov_b32_e32 v83, v1
	v_add_f32_e32 v71, v62, v216
	v_add_f32_e32 v72, v58, v220
	v_add_f32_e32 v73, v63, v217
	v_add_f32_e32 v76, v59, v221
	v_mul_f32_e32 v71, 0xbfb8aa3b, v71
	v_mul_f32_e32 v72, 0xbfb8aa3b, v72
	v_mul_f32_e32 v73, 0xbfb8aa3b, v73
	v_mul_f32_e32 v76, 0xbfb8aa3b, v76
	v_exp_f32_e32 v71, v71
	v_exp_f32_e32 v72, v72
	v_exp_f32_e32 v73, v73
	v_exp_f32_e32 v76, v76
	v_add_f32_e32 v74, v64, v218
	v_add_f32_e32 v77, v60, v222
	v_add_f32_e32 v75, v65, v219
	v_add_f32_e32 v78, v61, v223
	v_mul_f32_e32 v74, 0xbfb8aa3b, v74
	v_mul_f32_e32 v77, 0xbfb8aa3b, v77
	v_mul_f32_e32 v75, 0xbfb8aa3b, v75
	v_mul_f32_e32 v78, 0xbfb8aa3b, v78
	v_exp_f32_e32 v74, v74
	v_exp_f32_e32 v77, v77
	v_exp_f32_e32 v75, v75
	v_exp_f32_e32 v78, v78
	v_add_f32_e32 v71, 1.0, v71
	v_add_f32_e32 v72, 1.0, v72
	v_add_f32_e32 v73, 1.0, v73
	v_add_f32_e32 v76, 1.0, v76
	v_rcp_f32_e32 v71, v71
	v_rcp_f32_e32 v72, v72
	v_rcp_f32_e32 v73, v73
	v_rcp_f32_e32 v76, v76
	v_add_f32_e32 v74, 1.0, v74
	v_add_f32_e32 v77, 1.0, v77
	v_add_f32_e32 v75, 1.0, v75
	v_add_f32_e32 v78, 1.0, v78
	v_rcp_f32_e32 v74, v74
	v_rcp_f32_e32 v77, v77
	v_rcp_f32_e32 v75, v75
	v_rcp_f32_e32 v78, v78
	v_cvt_pk_fp8_f32 v82, v71, v73
	v_cvt_pk_fp8_f32 v83, v72, v76
	v_lshl_add_u64 v[72:73], s[54:55], 0, v[0:1]
	v_lshl_add_u64 v[72:73], v[72:73], 0, v[80:81]
	v_cvt_pk_fp8_f32 v82, v74, v75 op_sel:[0, 0, 1]
	v_cvt_pk_fp8_f32 v83, v77, v78 op_sel:[0, 0, 1]
	global_store_dwordx2 v[72:73], v[82:83], off

; #define EGAS __attribute__((address_space(1)))
; __device__ __forceinline__ float sigm(float x) { return __builtin_amdgcn_rcpf(1.f + __expf(-x)); }
;     __device__ __forceinline__ void operator()(const f32x4 (&acc)[2][2][4][2], const Unit& u, int wr, int wc, int fr, int fq) const {
;     ...
;                     if constexpr (MODE == EP_IN) {
;                         if (pn < 12) {
;                             rope8(v0, v1, WSF(WS_ROPEA) + (row * 64 + (cw >> 1)) * 2);
;                             EGAS bf16_t* O = pn < 6 ? WSB(WS_QA) : WSB(WS_KA); const int c = (pn < 6 ? pn : pn - 6) * 256 + ct;
;                             st8(O + row * WA + c, v0, v1);
;                         } else if (pn < 18) { st8(WSB(WS_VA) + row * WA + (pn - 12) * 256 + ct, v0, v1);
;                         } else if (pn < 20) { st8(WSB(WS_QL) + row * QLORA + (pn - 18) * 256 + ct, v0, v1);
;                         } else if (pn < 22) { st8(WSB(WS_KVL) + row * KVLORA + (pn - 20) * 256 + ct, v0, v1);
;                         } else if (pn < 38) {
;                             const int gc = (pn - 22) * 256 + ct; const EGAS float* bg = (const EGAS float*)p.f0; const f32x4 b0 = *(const EGAS f32x4*)(bg + gc), b1 = *(const EGAS f32x4*)(bg + gc + 4);
; #pragma unroll
;                             for (int e = 0; e < 4; ++e) { v0[e] = sigm(v0[e] + b0[e]); v1[e] = sigm(v1[e] + b1[e]); }
;                             st8f8(WS8(WS_GATES) + row * 4096 + gc, v0, v1);
.LBB0_516:
	v_lshl_or_b32 v70, v70, 7, v138
	v_mov_b32_e32 v71, v1
	s_andn2_b64 vcc, exec, s[36:37]
	v_lshl_add_u64 v[70:71], v[70:71], 2, s[62:63]
	s_cbranch_vccnz .LBB0_518
	s_add_u32 s36, s8, s17
	s_addc_u32 s37, s9, 0
	v_ashrrev_i32_e32 v123, 31, v122
	s_waitcnt vmcnt(12)
	v_pk_mul_f32 v[82:83], v[62:63], v[216:217]
	v_pk_mul_f32 v[62:63], v[62:63], v[216:217] op_sel:[1,0] op_sel_hi:[0,1]
	v_pk_mul_f32 v[80:81], v[64:65], v[218:219]
	v_add_f32_e32 v76, v62, v63
	v_pk_mul_f32 v[62:63], v[64:65], v[218:219] op_sel:[1,0] op_sel_hi:[0,1]
	v_pk_mul_f32 v[64:65], v[58:59], v[220:221]
	v_pk_mul_f32 v[58:59], v[58:59], v[220:221] op_sel:[1,0] op_sel_hi:[0,1]
	v_sub_f32_e32 v64, v64, v65
	v_add_f32_e32 v65, v58, v59
	v_pk_mul_f32 v[58:59], v[60:61], v[222:223] op_sel:[1,0] op_sel_hi:[0,1]
	v_add_f32_e32 v78, v62, v63
	v_pk_mul_f32 v[62:63], v[60:61], v[222:223]
	v_add_f32_e32 v61, v58, v59
	v_lshl_add_u64 v[58:59], v[66:67], 1, s[36:37]
	v_sub_f32_e32 v72, v62, v63
	v_lshl_add_u64 v[62:63], v[122:123], 1, v[58:59]
	v_sub_f32_e32 v82, v82, v83
	v_sub_f32_e32 v77, v80, v81
	v_cvt_pk_bf16_f32 v58, v82, v76
	v_cvt_pk_bf16_f32 v59, v77, v78
	v_cvt_pk_bf16_f32 v60, v64, v65
	v_cvt_pk_bf16_f32 v61, v72, v61
	global_store_dwordx4 v[62:63], v[58:61], off
.LBB0_518:
	v_mov_b32_e32 v157, v156
	s_nop 0
	v_mov_b32_e32 v58, v156
	v_mov_b32_e32 v59, v156
	v_pk_mul_f32 v[56:57], v[56:57], v[58:59]
	v_pk_mul_f32 v[54:55], v[54:55], v[156:157]
	v_pk_mul_f32 v[52:53], v[52:53], v[58:59]
	v_pk_mul_f32 v[50:51], v[50:51], v[156:157]
	s_and_b64 vcc, exec, s[44:45]
	s_mov_b64 s[36:37], -1
	s_cbranch_vccnz .LBB0_534
	s_and_b64 vcc, exec, s[42:43]
	s_cbranch_vccnz .LBB0_531
	s_andn2_b64 vcc, exec, s[30:31]
	s_cbranch_vccnz .LBB0_528
	s_andn2_b64 vcc, exec, s[28:29]
	s_cbranch_vccnz .LBB0_525
	s_andn2_b64 vcc, exec, s[26:27]
	s_cbranch_vccnz .LBB0_524
	v_or_b32_e32 v58, s19, v140
	v_mov_b32_e32 v59, v1
	v_mov_b32_e32 v72, v1
	v_mov_b32_e32 v73, v1
	v_add_f32_e32 v58, v54, v224
	v_add_f32_e32 v62, v50, v228
	v_add_f32_e32 v59, v55, v225
	v_add_f32_e32 v63, v51, v229
	v_mul_f32_e32 v58, 0xbfb8aa3b, v58
	v_mul_f32_e32 v62, 0xbfb8aa3b, v62
	v_mul_f32_e32 v59, 0xbfb8aa3b, v59
	v_mul_f32_e32 v63, 0xbfb8aa3b, v63
	v_exp_f32_e32 v58, v58
	v_exp_f32_e32 v62, v62
	v_exp_f32_e32 v59, v59
	v_exp_f32_e32 v63, v63
	v_add_f32_e32 v60, v56, v226
	v_add_f32_e32 v64, v52, v230
	v_add_f32_e32 v61, v57, v227
	v_add_f32_e32 v65, v53, v231
	v_mul_f32_e32 v60, 0xbfb8aa3b, v60
	v_mul_f32_e32 v64, 0xbfb8aa3b, v64
	v_mul_f32_e32 v61, 0xbfb8aa3b, v61
	v_mul_f32_e32 v65, 0xbfb8aa3b, v65
	v_exp_f32_e32 v60, v60
	v_exp_f32_e32 v64, v64
	v_exp_f32_e32 v61, v61
	v_exp_f32_e32 v65, v65
	v_add_f32_e32 v58, 1.0, v58
	v_add_f32_e32 v62, 1.0, v62
	v_add_f32_e32 v59, 1.0, v59
	v_add_f32_e32 v63, 1.0, v63
	v_rcp_f32_e32 v58, v58
	v_rcp_f32_e32 v62, v62
	v_rcp_f32_e32 v59, v59
	v_rcp_f32_e32 v63, v63
	v_add_f32_e32 v60, 1.0, v60
	v_add_f32_e32 v64, 1.0, v64
	v_add_f32_e32 v61, 1.0, v61
	v_add_f32_e32 v65, 1.0, v65
	v_rcp_f32_e32 v60, v60
	v_rcp_f32_e32 v64, v64
	v_rcp_f32_e32 v61, v61
	v_rcp_f32_e32 v65, v65
	v_cvt_pk_fp8_f32 v72, v58, v59
	v_cvt_pk_fp8_f32 v73, v62, v63
	v_lshl_add_u64 v[58:59], s[54:55], 0, v[0:1]
	v_cvt_pk_fp8_f32 v72, v60, v61 op_sel:[0, 0, 1]
	v_cvt_pk_fp8_f32 v73, v64, v65 op_sel:[0, 0, 1]
	v_add_u32_e32 v60, s19, v138
	v_mov_b32_e32 v61, v1
	v_lshl_add_u64 v[58:59], v[58:59], 0, v[60:61]
	global_store_dwordx2 v[58:59], v[72:73], off offset:128

; #define EGAS __attribute__((address_space(1)))
;     __device__ __forceinline__ void operator()(const f32x4 (&acc)[2][2][4][2], const Unit& u, int wr, int wc, int fr, int fq) const {
;     ...
;                         if (pn < 12) {
;                             rope8(v0, v1, WSF(WS_ROPEA) + (row * 64 + (cw >> 1)) * 2);
;                             EGAS bf16_t* O = pn < 6 ? WSB(WS_QA) : WSB(WS_KA); const int c = (pn < 6 ? pn : pn - 6) * 256 + ct;
;                             st8(O + row * WA + c, v0, v1);
.LBB0_534:
	s_andn2_b64 vcc, exec, s[36:37]
	s_cbranch_vccnz .LBB0_536
	s_add_u32 s36, s8, s17
	s_addc_u32 s37, s9, 0
	s_ashr_i32 s25, s24, 31
	v_pk_mul_f32 v[70:71], v[54:55], v[216:217]
	v_pk_mul_f32 v[54:55], v[54:55], v[216:217] op_sel:[1,0] op_sel_hi:[0,1]
	v_pk_mul_f32 v[68:69], v[56:57], v[218:219]
	v_add_f32_e32 v62, v54, v55
	v_pk_mul_f32 v[54:55], v[56:57], v[218:219] op_sel:[1,0] op_sel_hi:[0,1]
	v_pk_mul_f32 v[56:57], v[50:51], v[220:221]
	v_pk_mul_f32 v[50:51], v[50:51], v[220:221] op_sel:[1,0] op_sel_hi:[0,1]
	v_sub_f32_e32 v56, v56, v57
	v_add_f32_e32 v57, v50, v51
	v_pk_mul_f32 v[50:51], v[52:53], v[222:223] op_sel:[1,0] op_sel_hi:[0,1]
	v_add_f32_e32 v64, v54, v55
	v_pk_mul_f32 v[54:55], v[52:53], v[222:223]
	v_add_f32_e32 v59, v50, v51
	v_lshl_add_u64 v[50:51], v[66:67], 1, s[36:37]
	v_lshl_add_u64 v[52:53], s[24:25], 0, v[138:139]
	v_sub_f32_e32 v58, v54, v55
	v_lshl_add_u64 v[54:55], v[52:53], 1, v[50:51]
	v_sub_f32_e32 v0, v70, v71
	v_sub_f32_e32 v63, v68, v69
	v_cvt_pk_bf16_f32 v50, v0, v62
	v_cvt_pk_bf16_f32 v51, v63, v64
	v_cvt_pk_bf16_f32 v52, v56, v57
	v_cvt_pk_bf16_f32 v53, v58, v59
	global_store_dwordx4 v[54:55], v[50:53], off offset:256

; #define EGAS __attribute__((address_space(1)))
; __device__ __forceinline__ float sigm(float x) { return __builtin_amdgcn_rcpf(1.f + __expf(-x)); }
; __device__ __forceinline__ void st8f8(EGAS unsigned char* dst, f32x4 v0, f32x4 v1) {
;     int w0 = __builtin_amdgcn_cvt_pk_fp8_f32(v0[0], v0[1], 0, false); w0 = __builtin_amdgcn_cvt_pk_fp8_f32(v0[2], v0[3], w0, true);
;     int w1 = __builtin_amdgcn_cvt_pk_fp8_f32(v1[0], v1[1], 0, false); w1 = __builtin_amdgcn_cvt_pk_fp8_f32(v1[2], v1[3], w1, true);
;     *(EGAS u32x2e*)dst = (u32x2e){(unsigned)w0, (unsigned)w1}; }
;     __device__ __forceinline__ void operator()(const f32x4 (&acc)[2][2][4][2], const Unit& u, int wr, int wc, int fr, int fq) const {
;     ...
;                         } else if (pn < 38) {
;                             const int gc = (pn - 22) * 256 + ct; const EGAS float* bg = (const EGAS float*)p.f0; const f32x4 b0 = *(const EGAS f32x4*)(bg + gc), b1 = *(const EGAS f32x4*)(bg + gc + 4);
; #pragma unroll
;                             for (int e = 0; e < 4; ++e) { v0[e] = sigm(v0[e] + b0[e]); v1[e] = sigm(v1[e] + b1[e]); }
;                             st8f8(WS8(WS_GATES) + row * 4096 + gc, v0, v1);
.LBB0_544:
	s_andn2_b64 vcc, exec, s[36:37]
	s_cbranch_vccnz .LBB0_546
	v_or_b32_e32 v64, s19, v138
	v_mov_b32_e32 v65, v1
	v_mov_b32_e32 v66, v1
	v_mov_b32_e32 v67, v1
	v_add_f32_e32 v55, v46, v216
	v_add_f32_e32 v56, v42, v220
	v_add_f32_e32 v57, v47, v217
	v_add_f32_e32 v60, v43, v221
	v_mul_f32_e32 v55, 0xbfb8aa3b, v55
	v_mul_f32_e32 v56, 0xbfb8aa3b, v56
	v_mul_f32_e32 v57, 0xbfb8aa3b, v57
	v_mul_f32_e32 v60, 0xbfb8aa3b, v60
	v_exp_f32_e32 v55, v55
	v_exp_f32_e32 v56, v56
	v_exp_f32_e32 v57, v57
	v_exp_f32_e32 v60, v60
	v_add_f32_e32 v58, v48, v218
	v_add_f32_e32 v61, v44, v222
	v_add_f32_e32 v59, v49, v219
	v_add_f32_e32 v62, v45, v223
	v_mul_f32_e32 v58, 0xbfb8aa3b, v58
	v_mul_f32_e32 v61, 0xbfb8aa3b, v61
	v_mul_f32_e32 v59, 0xbfb8aa3b, v59
	v_mul_f32_e32 v62, 0xbfb8aa3b, v62
	v_exp_f32_e32 v58, v58
	v_exp_f32_e32 v61, v61
	v_exp_f32_e32 v59, v59
	v_exp_f32_e32 v62, v62
	v_add_f32_e32 v55, 1.0, v55
	v_add_f32_e32 v56, 1.0, v56
	v_add_f32_e32 v57, 1.0, v57
	v_add_f32_e32 v60, 1.0, v60
	v_rcp_f32_e32 v55, v55
	v_rcp_f32_e32 v56, v56
	v_rcp_f32_e32 v57, v57
	v_rcp_f32_e32 v60, v60
	v_add_f32_e32 v58, 1.0, v58
	v_add_f32_e32 v61, 1.0, v61
	v_add_f32_e32 v59, 1.0, v59
	v_add_f32_e32 v62, 1.0, v62
	v_rcp_f32_e32 v58, v58
	v_rcp_f32_e32 v61, v61
	v_rcp_f32_e32 v59, v59
	v_rcp_f32_e32 v62, v62
	v_cvt_pk_fp8_f32 v66, v55, v57
	v_cvt_pk_fp8_f32 v67, v56, v60
	v_lshl_add_u64 v[56:57], s[54:55], 0, v[0:1]
	v_lshl_add_u64 v[56:57], v[56:57], 0, v[64:65]
	v_cvt_pk_fp8_f32 v66, v58, v59 op_sel:[0, 0, 1]
	v_cvt_pk_fp8_f32 v67, v61, v62 op_sel:[0, 0, 1]
	global_store_dwordx2 v[56:57], v[66:67], off

; #define EGAS __attribute__((address_space(1)))
; __device__ __forceinline__ float sigm(float x) { return __builtin_amdgcn_rcpf(1.f + __expf(-x)); }
;     __device__ __forceinline__ void operator()(const f32x4 (&acc)[2][2][4][2], const Unit& u, int wr, int wc, int fr, int fq) const {
;     ...
;                     if constexpr (MODE == EP_IN) {
;                         if (pn < 12) {
;                             rope8(v0, v1, WSF(WS_ROPEA) + (row * 64 + (cw >> 1)) * 2);
;                             EGAS bf16_t* O = pn < 6 ? WSB(WS_QA) : WSB(WS_KA); const int c = (pn < 6 ? pn : pn - 6) * 256 + ct;
;                             st8(O + row * WA + c, v0, v1);
;                         } else if (pn < 18) { st8(WSB(WS_VA) + row * WA + (pn - 12) * 256 + ct, v0, v1);
;                         } else if (pn < 20) { st8(WSB(WS_QL) + row * QLORA + (pn - 18) * 256 + ct, v0, v1);
;                         } else if (pn < 22) { st8(WSB(WS_KVL) + row * KVLORA + (pn - 20) * 256 + ct, v0, v1);
;                         } else if (pn < 38) {
;                             const int gc = (pn - 22) * 256 + ct; const EGAS float* bg = (const EGAS float*)p.f0; const f32x4 b0 = *(const EGAS f32x4*)(bg + gc), b1 = *(const EGAS f32x4*)(bg + gc + 4);
; #pragma unroll
;                             for (int e = 0; e < 4; ++e) { v0[e] = sigm(v0[e] + b0[e]); v1[e] = sigm(v1[e] + b1[e]); }
;                             st8f8(WS8(WS_GATES) + row * 4096 + gc, v0, v1);
.LBB0_556:
	v_lshl_or_b32 v54, v54, 7, v138
	v_mov_b32_e32 v55, v1
	s_andn2_b64 vcc, exec, s[36:37]
	v_lshl_add_u64 v[54:55], v[54:55], 2, s[62:63]
	s_cbranch_vccnz .LBB0_558
	s_add_u32 s36, s8, s17
	s_addc_u32 s37, s9, 0
	v_ashrrev_i32_e32 v123, 31, v122
	s_waitcnt vmcnt(10)
	v_pk_mul_f32 v[66:67], v[46:47], v[224:225]
	v_pk_mul_f32 v[46:47], v[46:47], v[224:225] op_sel:[1,0] op_sel_hi:[0,1]
	v_pk_mul_f32 v[64:65], v[48:49], v[226:227]
	v_add_f32_e32 v60, v46, v47
	v_pk_mul_f32 v[46:47], v[48:49], v[226:227] op_sel:[1,0] op_sel_hi:[0,1]
	v_pk_mul_f32 v[48:49], v[42:43], v[228:229]
	v_pk_mul_f32 v[42:43], v[42:43], v[228:229] op_sel:[1,0] op_sel_hi:[0,1]
	v_sub_f32_e32 v48, v48, v49
	v_add_f32_e32 v49, v42, v43
	v_pk_mul_f32 v[42:43], v[44:45], v[230:231] op_sel:[1,0] op_sel_hi:[0,1]
	v_add_f32_e32 v62, v46, v47
	v_pk_mul_f32 v[46:47], v[44:45], v[230:231]
	v_add_f32_e32 v45, v42, v43
	v_lshl_add_u64 v[42:43], v[50:51], 1, s[36:37]
	v_sub_f32_e32 v56, v46, v47
	v_lshl_add_u64 v[46:47], v[122:123], 1, v[42:43]
	v_sub_f32_e32 v66, v66, v67
	v_sub_f32_e32 v61, v64, v65
	v_cvt_pk_bf16_f32 v42, v66, v60
	v_cvt_pk_bf16_f32 v43, v61, v62
	v_cvt_pk_bf16_f32 v44, v48, v49
	v_cvt_pk_bf16_f32 v45, v56, v45
	global_store_dwordx4 v[46:47], v[42:45], off
.LBB0_558:
	v_mov_b32_e32 v155, v154
	s_nop 0
	v_mov_b32_e32 v42, v154
	v_mov_b32_e32 v43, v154
	v_pk_mul_f32 v[40:41], v[40:41], v[42:43]
	v_pk_mul_f32 v[38:39], v[38:39], v[154:155]
	v_pk_mul_f32 v[36:37], v[36:37], v[42:43]
	v_pk_mul_f32 v[34:35], v[34:35], v[154:155]
	s_and_b64 vcc, exec, s[44:45]
	s_mov_b64 s[36:37], -1
	s_cbranch_vccnz .LBB0_574
	s_and_b64 vcc, exec, s[42:43]
	s_cbranch_vccnz .LBB0_571
	s_andn2_b64 vcc, exec, s[30:31]
	s_cbranch_vccnz .LBB0_568
	s_andn2_b64 vcc, exec, s[28:29]
	s_cbranch_vccnz .LBB0_565
	s_andn2_b64 vcc, exec, s[26:27]
	s_cbranch_vccnz .LBB0_564
	v_or_b32_e32 v42, s19, v140
	v_mov_b32_e32 v43, v1
	v_mov_b32_e32 v56, v1
	v_mov_b32_e32 v57, v1
	v_add_f32_e32 v42, v38, v224
	v_add_f32_e32 v46, v34, v228
	v_add_f32_e32 v43, v39, v225
	v_add_f32_e32 v47, v35, v229
	v_mul_f32_e32 v42, 0xbfb8aa3b, v42
	v_mul_f32_e32 v46, 0xbfb8aa3b, v46
	v_mul_f32_e32 v43, 0xbfb8aa3b, v43
	v_mul_f32_e32 v47, 0xbfb8aa3b, v47
	v_exp_f32_e32 v42, v42
	v_exp_f32_e32 v46, v46
	v_exp_f32_e32 v43, v43
	v_exp_f32_e32 v47, v47
	v_add_f32_e32 v44, v40, v226
	v_add_f32_e32 v48, v36, v230
	v_add_f32_e32 v45, v41, v227
	v_add_f32_e32 v49, v37, v231
	v_mul_f32_e32 v44, 0xbfb8aa3b, v44
	v_mul_f32_e32 v48, 0xbfb8aa3b, v48
	v_mul_f32_e32 v45, 0xbfb8aa3b, v45
	v_mul_f32_e32 v49, 0xbfb8aa3b, v49
	v_exp_f32_e32 v44, v44
	v_exp_f32_e32 v48, v48
	v_exp_f32_e32 v45, v45
	v_exp_f32_e32 v49, v49
	v_add_f32_e32 v42, 1.0, v42
	v_add_f32_e32 v46, 1.0, v46
	v_add_f32_e32 v43, 1.0, v43
	v_add_f32_e32 v47, 1.0, v47
	v_rcp_f32_e32 v42, v42
	v_rcp_f32_e32 v46, v46
	v_rcp_f32_e32 v43, v43
	v_rcp_f32_e32 v47, v47
	v_add_f32_e32 v44, 1.0, v44
	v_add_f32_e32 v48, 1.0, v48
	v_add_f32_e32 v45, 1.0, v45
	v_add_f32_e32 v49, 1.0, v49
	v_rcp_f32_e32 v44, v44
	v_rcp_f32_e32 v48, v48
	v_rcp_f32_e32 v45, v45
	v_rcp_f32_e32 v49, v49
	v_cvt_pk_fp8_f32 v56, v42, v43
	v_cvt_pk_fp8_f32 v57, v46, v47
	v_lshl_add_u64 v[42:43], s[54:55], 0, v[0:1]
	v_cvt_pk_fp8_f32 v56, v44, v45 op_sel:[0, 0, 1]
	v_cvt_pk_fp8_f32 v57, v48, v49 op_sel:[0, 0, 1]
	v_add_u32_e32 v44, s19, v138
	v_mov_b32_e32 v45, v1
	v_lshl_add_u64 v[42:43], v[42:43], 0, v[44:45]
	global_store_dwordx2 v[42:43], v[56:57], off offset:128

; #define EGAS __attribute__((address_space(1)))
;     __device__ __forceinline__ void operator()(const f32x4 (&acc)[2][2][4][2], const Unit& u, int wr, int wc, int fr, int fq) const {
;     ...
;                         if (pn < 12) {
;                             rope8(v0, v1, WSF(WS_ROPEA) + (row * 64 + (cw >> 1)) * 2);
;                             EGAS bf16_t* O = pn < 6 ? WSB(WS_QA) : WSB(WS_KA); const int c = (pn < 6 ? pn : pn - 6) * 256 + ct;
;                             st8(O + row * WA + c, v0, v1);
.LBB0_574:
	s_andn2_b64 vcc, exec, s[36:37]
	s_cbranch_vccnz .LBB0_576
	s_add_u32 s36, s8, s17
	s_addc_u32 s37, s9, 0
	s_ashr_i32 s25, s24, 31
	v_pk_mul_f32 v[54:55], v[38:39], v[224:225]
	v_pk_mul_f32 v[38:39], v[38:39], v[224:225] op_sel:[1,0] op_sel_hi:[0,1]
	v_pk_mul_f32 v[52:53], v[40:41], v[226:227]
	v_add_f32_e32 v46, v38, v39
	v_pk_mul_f32 v[38:39], v[40:41], v[226:227] op_sel:[1,0] op_sel_hi:[0,1]
	v_pk_mul_f32 v[40:41], v[34:35], v[228:229]
	v_pk_mul_f32 v[34:35], v[34:35], v[228:229] op_sel:[1,0] op_sel_hi:[0,1]
	v_sub_f32_e32 v40, v40, v41
	v_add_f32_e32 v41, v34, v35
	v_pk_mul_f32 v[34:35], v[36:37], v[230:231] op_sel:[1,0] op_sel_hi:[0,1]
	v_add_f32_e32 v48, v38, v39
	v_pk_mul_f32 v[38:39], v[36:37], v[230:231]
	v_add_f32_e32 v43, v34, v35
	v_lshl_add_u64 v[34:35], v[50:51], 1, s[36:37]
	v_lshl_add_u64 v[36:37], s[24:25], 0, v[138:139]
	v_sub_f32_e32 v42, v38, v39
	v_lshl_add_u64 v[38:39], v[36:37], 1, v[34:35]
	v_sub_f32_e32 v0, v54, v55
	v_sub_f32_e32 v47, v52, v53
	v_cvt_pk_bf16_f32 v34, v0, v46
	v_cvt_pk_bf16_f32 v35, v47, v48
	v_cvt_pk_bf16_f32 v36, v40, v41
	v_cvt_pk_bf16_f32 v37, v42, v43
	global_store_dwordx4 v[38:39], v[34:37], off offset:256

; #define EGAS __attribute__((address_space(1)))
; __device__ __forceinline__ float sigm(float x) { return __builtin_amdgcn_rcpf(1.f + __expf(-x)); }
; __device__ __forceinline__ void st8f8(EGAS unsigned char* dst, f32x4 v0, f32x4 v1) {
;     int w0 = __builtin_amdgcn_cvt_pk_fp8_f32(v0[0], v0[1], 0, false); w0 = __builtin_amdgcn_cvt_pk_fp8_f32(v0[2], v0[3], w0, true);
;     int w1 = __builtin_amdgcn_cvt_pk_fp8_f32(v1[0], v1[1], 0, false); w1 = __builtin_amdgcn_cvt_pk_fp8_f32(v1[2], v1[3], w1, true);
;     *(EGAS u32x2e*)dst = (u32x2e){(unsigned)w0, (unsigned)w1}; }
;     __device__ __forceinline__ void operator()(const f32x4 (&acc)[2][2][4][2], const Unit& u, int wr, int wc, int fr, int fq) const {
;     ...
;                         } else if (pn < 38) {
;                             const int gc = (pn - 22) * 256 + ct; const EGAS float* bg = (const EGAS float*)p.f0; const f32x4 b0 = *(const EGAS f32x4*)(bg + gc), b1 = *(const EGAS f32x4*)(bg + gc + 4);
; #pragma unroll
;                             for (int e = 0; e < 4; ++e) { v0[e] = sigm(v0[e] + b0[e]); v1[e] = sigm(v1[e] + b1[e]); }
;                             st8f8(WS8(WS_GATES) + row * 4096 + gc, v0, v1);
.LBB0_584:
	s_andn2_b64 vcc, exec, s[36:37]
	s_cbranch_vccnz .LBB0_586
	v_or_b32_e32 v48, s19, v138
	v_mov_b32_e32 v49, v1
	v_mov_b32_e32 v50, v1
	v_mov_b32_e32 v51, v1
	v_add_f32_e32 v39, v30, v216
	v_add_f32_e32 v40, v26, v220
	v_add_f32_e32 v41, v31, v217
	v_add_f32_e32 v44, v27, v221
	v_mul_f32_e32 v39, 0xbfb8aa3b, v39
	v_mul_f32_e32 v40, 0xbfb8aa3b, v40
	v_mul_f32_e32 v41, 0xbfb8aa3b, v41
	v_mul_f32_e32 v44, 0xbfb8aa3b, v44
	v_exp_f32_e32 v39, v39
	v_exp_f32_e32 v40, v40
	v_exp_f32_e32 v41, v41
	v_exp_f32_e32 v44, v44
	v_add_f32_e32 v42, v32, v218
	v_add_f32_e32 v45, v28, v222
	v_add_f32_e32 v43, v33, v219
	v_add_f32_e32 v46, v29, v223
	v_mul_f32_e32 v42, 0xbfb8aa3b, v42
	v_mul_f32_e32 v45, 0xbfb8aa3b, v45
	v_mul_f32_e32 v43, 0xbfb8aa3b, v43
	v_mul_f32_e32 v46, 0xbfb8aa3b, v46
	v_exp_f32_e32 v42, v42
	v_exp_f32_e32 v45, v45
	v_exp_f32_e32 v43, v43
	v_exp_f32_e32 v46, v46
	v_add_f32_e32 v39, 1.0, v39
	v_add_f32_e32 v40, 1.0, v40
	v_add_f32_e32 v41, 1.0, v41
	v_add_f32_e32 v44, 1.0, v44
	v_rcp_f32_e32 v39, v39
	v_rcp_f32_e32 v40, v40
	v_rcp_f32_e32 v41, v41
	v_rcp_f32_e32 v44, v44
	v_add_f32_e32 v42, 1.0, v42
	v_add_f32_e32 v45, 1.0, v45
	v_add_f32_e32 v43, 1.0, v43
	v_add_f32_e32 v46, 1.0, v46
	v_rcp_f32_e32 v42, v42
	v_rcp_f32_e32 v45, v45
	v_rcp_f32_e32 v43, v43
	v_rcp_f32_e32 v46, v46
	v_cvt_pk_fp8_f32 v50, v39, v41
	v_cvt_pk_fp8_f32 v51, v40, v44
	v_lshl_add_u64 v[40:41], s[54:55], 0, v[0:1]
	v_lshl_add_u64 v[40:41], v[40:41], 0, v[48:49]
	v_cvt_pk_fp8_f32 v50, v42, v43 op_sel:[0, 0, 1]
	v_cvt_pk_fp8_f32 v51, v45, v46 op_sel:[0, 0, 1]
	global_store_dwordx2 v[40:41], v[50:51], off

; #define EGAS __attribute__((address_space(1)))
; __device__ __forceinline__ float sigm(float x) { return __builtin_amdgcn_rcpf(1.f + __expf(-x)); }
;     __device__ __forceinline__ void operator()(const f32x4 (&acc)[2][2][4][2], const Unit& u, int wr, int wc, int fr, int fq) const {
;     ...
;                     if constexpr (MODE == EP_IN) {
;                         if (pn < 12) {
;                             rope8(v0, v1, WSF(WS_ROPEA) + (row * 64 + (cw >> 1)) * 2);
;                             EGAS bf16_t* O = pn < 6 ? WSB(WS_QA) : WSB(WS_KA); const int c = (pn < 6 ? pn : pn - 6) * 256 + ct;
;                             st8(O + row * WA + c, v0, v1);
;                         } else if (pn < 18) { st8(WSB(WS_VA) + row * WA + (pn - 12) * 256 + ct, v0, v1);
;                         } else if (pn < 20) { st8(WSB(WS_QL) + row * QLORA + (pn - 18) * 256 + ct, v0, v1);
;                         } else if (pn < 22) { st8(WSB(WS_KVL) + row * KVLORA + (pn - 20) * 256 + ct, v0, v1);
;                         } else if (pn < 38) {
;                             const int gc = (pn - 22) * 256 + ct; const EGAS float* bg = (const EGAS float*)p.f0; const f32x4 b0 = *(const EGAS f32x4*)(bg + gc), b1 = *(const EGAS f32x4*)(bg + gc + 4);
; #pragma unroll
;                             for (int e = 0; e < 4; ++e) { v0[e] = sigm(v0[e] + b0[e]); v1[e] = sigm(v1[e] + b1[e]); }
;                             st8f8(WS8(WS_GATES) + row * 4096 + gc, v0, v1);
.LBB0_596:
	v_lshl_or_b32 v38, v38, 7, v138
	v_mov_b32_e32 v39, v1
	s_andn2_b64 vcc, exec, s[36:37]
	v_lshl_add_u64 v[38:39], v[38:39], 2, s[62:63]
	s_cbranch_vccnz .LBB0_598
	s_add_u32 s36, s8, s17
	s_addc_u32 s37, s9, 0
	v_ashrrev_i32_e32 v123, 31, v122
	s_waitcnt vmcnt(8)
	v_pk_mul_f32 v[50:51], v[30:31], v[232:233]
	v_pk_mul_f32 v[30:31], v[30:31], v[232:233] op_sel:[1,0] op_sel_hi:[0,1]
	v_pk_mul_f32 v[48:49], v[32:33], v[234:235]
	v_add_f32_e32 v44, v30, v31
	v_pk_mul_f32 v[30:31], v[32:33], v[234:235] op_sel:[1,0] op_sel_hi:[0,1]
	v_pk_mul_f32 v[32:33], v[26:27], v[236:237]
	v_pk_mul_f32 v[26:27], v[26:27], v[236:237] op_sel:[1,0] op_sel_hi:[0,1]
	v_sub_f32_e32 v32, v32, v33
	v_add_f32_e32 v33, v26, v27
	v_pk_mul_f32 v[26:27], v[28:29], v[238:239] op_sel:[1,0] op_sel_hi:[0,1]
	v_add_f32_e32 v46, v30, v31
	v_pk_mul_f32 v[30:31], v[28:29], v[238:239]
	v_add_f32_e32 v29, v26, v27
	v_lshl_add_u64 v[26:27], v[34:35], 1, s[36:37]
	v_sub_f32_e32 v40, v30, v31
	v_lshl_add_u64 v[30:31], v[122:123], 1, v[26:27]
	v_sub_f32_e32 v50, v50, v51
	v_sub_f32_e32 v45, v48, v49
	v_cvt_pk_bf16_f32 v26, v50, v44
	v_cvt_pk_bf16_f32 v27, v45, v46
	v_cvt_pk_bf16_f32 v28, v32, v33
	v_cvt_pk_bf16_f32 v29, v40, v29
	global_store_dwordx4 v[30:31], v[26:29], off
.LBB0_598:
	v_mov_b32_e32 v153, v152
	s_nop 0
	v_mov_b32_e32 v26, v152
	v_mov_b32_e32 v27, v152
	v_pk_mul_f32 v[24:25], v[24:25], v[26:27]
	v_pk_mul_f32 v[22:23], v[22:23], v[152:153]
	v_pk_mul_f32 v[20:21], v[20:21], v[26:27]
	v_pk_mul_f32 v[18:19], v[18:19], v[152:153]
	s_and_b64 vcc, exec, s[44:45]
	s_mov_b64 s[36:37], -1
	s_cbranch_vccnz .LBB0_614
	s_and_b64 vcc, exec, s[42:43]
	s_cbranch_vccnz .LBB0_611
	s_andn2_b64 vcc, exec, s[30:31]
	s_cbranch_vccnz .LBB0_608
	s_andn2_b64 vcc, exec, s[28:29]
	s_cbranch_vccnz .LBB0_605
	s_andn2_b64 vcc, exec, s[26:27]
	s_cbranch_vccnz .LBB0_604
	v_or_b32_e32 v26, s19, v140
	v_mov_b32_e32 v27, v1
	v_mov_b32_e32 v40, v1
	v_mov_b32_e32 v41, v1
	v_add_f32_e32 v26, v22, v224
	v_add_f32_e32 v30, v18, v228
	v_add_f32_e32 v27, v23, v225
	v_add_f32_e32 v31, v19, v229
	v_mul_f32_e32 v26, 0xbfb8aa3b, v26
	v_mul_f32_e32 v30, 0xbfb8aa3b, v30
	v_mul_f32_e32 v27, 0xbfb8aa3b, v27
	v_mul_f32_e32 v31, 0xbfb8aa3b, v31
	v_exp_f32_e32 v26, v26
	v_exp_f32_e32 v30, v30
	v_exp_f32_e32 v27, v27
	v_exp_f32_e32 v31, v31
	v_add_f32_e32 v28, v24, v226
	v_add_f32_e32 v32, v20, v230
	v_add_f32_e32 v29, v25, v227
	v_add_f32_e32 v33, v21, v231
	v_mul_f32_e32 v28, 0xbfb8aa3b, v28
	v_mul_f32_e32 v32, 0xbfb8aa3b, v32
	v_mul_f32_e32 v29, 0xbfb8aa3b, v29
	v_mul_f32_e32 v33, 0xbfb8aa3b, v33
	v_exp_f32_e32 v28, v28
	v_exp_f32_e32 v32, v32
	v_exp_f32_e32 v29, v29
	v_exp_f32_e32 v33, v33
	v_add_f32_e32 v26, 1.0, v26
	v_add_f32_e32 v30, 1.0, v30
	v_add_f32_e32 v27, 1.0, v27
	v_add_f32_e32 v31, 1.0, v31
	v_rcp_f32_e32 v26, v26
	v_rcp_f32_e32 v30, v30
	v_rcp_f32_e32 v27, v27
	v_rcp_f32_e32 v31, v31
	v_add_f32_e32 v28, 1.0, v28
	v_add_f32_e32 v32, 1.0, v32
	v_add_f32_e32 v29, 1.0, v29
	v_add_f32_e32 v33, 1.0, v33
	v_rcp_f32_e32 v28, v28
	v_rcp_f32_e32 v32, v32
	v_rcp_f32_e32 v29, v29
	v_rcp_f32_e32 v33, v33
	v_cvt_pk_fp8_f32 v40, v26, v27
	v_cvt_pk_fp8_f32 v41, v30, v31
	v_lshl_add_u64 v[26:27], s[54:55], 0, v[0:1]
	v_cvt_pk_fp8_f32 v40, v28, v29 op_sel:[0, 0, 1]
	v_cvt_pk_fp8_f32 v41, v32, v33 op_sel:[0, 0, 1]
	v_add_u32_e32 v28, s19, v138
	v_mov_b32_e32 v29, v1
	v_lshl_add_u64 v[26:27], v[26:27], 0, v[28:29]
	global_store_dwordx2 v[26:27], v[40:41], off offset:128

; #define EGAS __attribute__((address_space(1)))
;     __device__ __forceinline__ void operator()(const f32x4 (&acc)[2][2][4][2], const Unit& u, int wr, int wc, int fr, int fq) const {
;     ...
;                         if (pn < 12) {
;                             rope8(v0, v1, WSF(WS_ROPEA) + (row * 64 + (cw >> 1)) * 2);
;                             EGAS bf16_t* O = pn < 6 ? WSB(WS_QA) : WSB(WS_KA); const int c = (pn < 6 ? pn : pn - 6) * 256 + ct;
;                             st8(O + row * WA + c, v0, v1);
.LBB0_614:
	s_andn2_b64 vcc, exec, s[36:37]
	s_cbranch_vccnz .LBB0_616
	s_add_u32 s36, s8, s17
	s_addc_u32 s37, s9, 0
	s_ashr_i32 s25, s24, 31
	v_pk_mul_f32 v[38:39], v[22:23], v[232:233]
	v_pk_mul_f32 v[22:23], v[22:23], v[232:233] op_sel:[1,0] op_sel_hi:[0,1]
	v_pk_mul_f32 v[36:37], v[24:25], v[234:235]
	v_add_f32_e32 v30, v22, v23
	v_pk_mul_f32 v[22:23], v[24:25], v[234:235] op_sel:[1,0] op_sel_hi:[0,1]
	v_pk_mul_f32 v[24:25], v[18:19], v[236:237]
	v_pk_mul_f32 v[18:19], v[18:19], v[236:237] op_sel:[1,0] op_sel_hi:[0,1]
	v_sub_f32_e32 v24, v24, v25
	v_add_f32_e32 v25, v18, v19
	v_pk_mul_f32 v[18:19], v[20:21], v[238:239] op_sel:[1,0] op_sel_hi:[0,1]
	v_add_f32_e32 v32, v22, v23
	v_pk_mul_f32 v[22:23], v[20:21], v[238:239]
	v_add_f32_e32 v27, v18, v19
	v_lshl_add_u64 v[18:19], v[34:35], 1, s[36:37]
	v_lshl_add_u64 v[20:21], s[24:25], 0, v[138:139]
	v_sub_f32_e32 v26, v22, v23
	v_lshl_add_u64 v[22:23], v[20:21], 1, v[18:19]
	v_sub_f32_e32 v0, v38, v39
	v_sub_f32_e32 v31, v36, v37
	v_cvt_pk_bf16_f32 v18, v0, v30
	v_cvt_pk_bf16_f32 v19, v31, v32
	v_cvt_pk_bf16_f32 v20, v24, v25
	v_cvt_pk_bf16_f32 v21, v26, v27
	global_store_dwordx4 v[22:23], v[18:21], off offset:256

; #define EGAS __attribute__((address_space(1)))
; __device__ __forceinline__ float sigm(float x) { return __builtin_amdgcn_rcpf(1.f + __expf(-x)); }
; __device__ __forceinline__ void st8f8(EGAS unsigned char* dst, f32x4 v0, f32x4 v1) {
;     int w0 = __builtin_amdgcn_cvt_pk_fp8_f32(v0[0], v0[1], 0, false); w0 = __builtin_amdgcn_cvt_pk_fp8_f32(v0[2], v0[3], w0, true);
;     int w1 = __builtin_amdgcn_cvt_pk_fp8_f32(v1[0], v1[1], 0, false); w1 = __builtin_amdgcn_cvt_pk_fp8_f32(v1[2], v1[3], w1, true);
;     *(EGAS u32x2e*)dst = (u32x2e){(unsigned)w0, (unsigned)w1}; }
;     __device__ __forceinline__ void operator()(const f32x4 (&acc)[2][2][4][2], const Unit& u, int wr, int wc, int fr, int fq) const {
;     ...
;                         } else if (pn < 38) {
;                             const int gc = (pn - 22) * 256 + ct; const EGAS float* bg = (const EGAS float*)p.f0; const f32x4 b0 = *(const EGAS f32x4*)(bg + gc), b1 = *(const EGAS f32x4*)(bg + gc + 4);
; #pragma unroll
;                             for (int e = 0; e < 4; ++e) { v0[e] = sigm(v0[e] + b0[e]); v1[e] = sigm(v1[e] + b1[e]); }
;                             st8f8(WS8(WS_GATES) + row * 4096 + gc, v0, v1);
.LBB0_624:
	s_andn2_b64 vcc, exec, s[34:35]
	s_cbranch_vccnz .LBB0_626
	v_or_b32_e32 v32, s19, v138
	v_mov_b32_e32 v33, v1
	v_mov_b32_e32 v34, v1
	v_mov_b32_e32 v35, v1
	v_add_f32_e32 v23, v14, v216
	v_add_f32_e32 v24, v10, v220
	v_add_f32_e32 v25, v15, v217
	v_add_f32_e32 v28, v11, v221
	v_mul_f32_e32 v23, 0xbfb8aa3b, v23
	v_mul_f32_e32 v24, 0xbfb8aa3b, v24
	v_mul_f32_e32 v25, 0xbfb8aa3b, v25
	v_mul_f32_e32 v28, 0xbfb8aa3b, v28
	v_exp_f32_e32 v23, v23
	v_exp_f32_e32 v24, v24
	v_exp_f32_e32 v25, v25
	v_exp_f32_e32 v28, v28
	v_add_f32_e32 v26, v16, v218
	v_add_f32_e32 v29, v12, v222
	v_add_f32_e32 v27, v17, v219
	v_add_f32_e32 v30, v13, v223
	v_mul_f32_e32 v26, 0xbfb8aa3b, v26
	v_mul_f32_e32 v29, 0xbfb8aa3b, v29
	v_mul_f32_e32 v27, 0xbfb8aa3b, v27
	v_mul_f32_e32 v30, 0xbfb8aa3b, v30
	v_exp_f32_e32 v26, v26
	v_exp_f32_e32 v29, v29
	v_exp_f32_e32 v27, v27
	v_exp_f32_e32 v30, v30
	v_add_f32_e32 v23, 1.0, v23
	v_add_f32_e32 v24, 1.0, v24
	v_add_f32_e32 v25, 1.0, v25
	v_add_f32_e32 v28, 1.0, v28
	v_rcp_f32_e32 v23, v23
	v_rcp_f32_e32 v24, v24
	v_rcp_f32_e32 v25, v25
	v_rcp_f32_e32 v28, v28
	v_add_f32_e32 v26, 1.0, v26
	v_add_f32_e32 v29, 1.0, v29
	v_add_f32_e32 v27, 1.0, v27
	v_add_f32_e32 v30, 1.0, v30
	v_rcp_f32_e32 v26, v26
	v_rcp_f32_e32 v29, v29
	v_rcp_f32_e32 v27, v27
	v_rcp_f32_e32 v30, v30
	v_cvt_pk_fp8_f32 v34, v23, v25
	v_cvt_pk_fp8_f32 v35, v24, v28
	v_lshl_add_u64 v[24:25], s[54:55], 0, v[0:1]
	v_lshl_add_u64 v[24:25], v[24:25], 0, v[32:33]
	v_cvt_pk_fp8_f32 v34, v26, v27 op_sel:[0, 0, 1]
	v_cvt_pk_fp8_f32 v35, v29, v30 op_sel:[0, 0, 1]
	global_store_dwordx2 v[24:25], v[34:35], off

; #define EGAS __attribute__((address_space(1)))
;     __device__ __forceinline__ void operator()(const f32x4 (&acc)[2][2][4][2], const Unit& u, int wr, int wc, int fr, int fq) const {
;     ...
;                         if (pn < 12) {
;                             rope8(v0, v1, WSF(WS_ROPEA) + (row * 64 + (cw >> 1)) * 2);
;                             EGAS bf16_t* O = pn < 6 ? WSB(WS_QA) : WSB(WS_KA); const int c = (pn < 6 ? pn : pn - 6) * 256 + ct;
;                             st8(O + row * WA + c, v0, v1);
.LBB0_636:
	v_lshl_or_b32 v22, v22, 7, v138
	v_mov_b32_e32 v23, v1
	s_andn2_b64 vcc, exec, s[36:37]
	v_lshl_add_u64 v[22:23], v[22:23], 2, s[62:63]
	s_cbranch_vccnz .LBB0_638
	s_add_u32 s34, s8, s17
	s_addc_u32 s35, s9, 0
	v_ashrrev_i32_e32 v123, 31, v122
	s_waitcnt vmcnt(6)
	v_pk_mul_f32 v[34:35], v[14:15], v[240:241]
	v_pk_mul_f32 v[14:15], v[14:15], v[240:241] op_sel:[1,0] op_sel_hi:[0,1]
	v_pk_mul_f32 v[32:33], v[16:17], v[242:243]
	v_add_f32_e32 v28, v14, v15
	v_pk_mul_f32 v[14:15], v[16:17], v[242:243] op_sel:[1,0] op_sel_hi:[0,1]
	v_pk_mul_f32 v[16:17], v[10:11], v[244:245]
	v_pk_mul_f32 v[10:11], v[10:11], v[244:245] op_sel:[1,0] op_sel_hi:[0,1]
	v_sub_f32_e32 v16, v16, v17
	v_add_f32_e32 v17, v10, v11
	v_pk_mul_f32 v[10:11], v[12:13], v[246:247] op_sel:[1,0] op_sel_hi:[0,1]
	v_add_f32_e32 v30, v14, v15
	v_pk_mul_f32 v[14:15], v[12:13], v[246:247]
	v_add_f32_e32 v13, v10, v11
	v_lshl_add_u64 v[10:11], v[18:19], 1, s[34:35]
	v_sub_f32_e32 v24, v14, v15
	v_lshl_add_u64 v[14:15], v[122:123], 1, v[10:11]
	v_sub_f32_e32 v34, v34, v35
	v_sub_f32_e32 v29, v32, v33
	v_cvt_pk_bf16_f32 v10, v34, v28
	v_cvt_pk_bf16_f32 v11, v29, v30
	v_cvt_pk_bf16_f32 v12, v16, v17
	v_cvt_pk_bf16_f32 v13, v24, v13
	global_store_dwordx4 v[14:15], v[10:13], off

; #define EGAS __attribute__((address_space(1)))
; __device__ __forceinline__ float sigm(float x) { return __builtin_amdgcn_rcpf(1.f + __expf(-x)); }
; __device__ __forceinline__ void st8f8(EGAS unsigned char* dst, f32x4 v0, f32x4 v1) {
;     int w0 = __builtin_amdgcn_cvt_pk_fp8_f32(v0[0], v0[1], 0, false); w0 = __builtin_amdgcn_cvt_pk_fp8_f32(v0[2], v0[3], w0, true);
;     int w1 = __builtin_amdgcn_cvt_pk_fp8_f32(v1[0], v1[1], 0, false); w1 = __builtin_amdgcn_cvt_pk_fp8_f32(v1[2], v1[3], w1, true);
;     *(EGAS u32x2e*)dst = (u32x2e){(unsigned)w0, (unsigned)w1}; }
;     __device__ __forceinline__ void operator()(const f32x4 (&acc)[2][2][4][2], const Unit& u, int wr, int wc, int fr, int fq) const {
;     ...
;                         } else if (pn < 38) {
;                             const int gc = (pn - 22) * 256 + ct; const EGAS float* bg = (const EGAS float*)p.f0; const f32x4 b0 = *(const EGAS f32x4*)(bg + gc), b1 = *(const EGAS f32x4*)(bg + gc + 4);
; #pragma unroll
;                             for (int e = 0; e < 4; ++e) { v0[e] = sigm(v0[e] + b0[e]); v1[e] = sigm(v1[e] + b1[e]); }
;                             st8f8(WS8(WS_GATES) + row * 4096 + gc, v0, v1);
.LBB0_641:
	s_and_b64 vcc, exec, s[42:43]
	s_cbranch_vccnz .LBB0_653
	s_andn2_b64 vcc, exec, s[30:31]
	s_mov_b64 s[30:31], -1
	s_cbranch_vccnz .LBB0_650
	s_andn2_b64 vcc, exec, s[28:29]
	s_mov_b64 s[28:29], -1
	s_cbranch_vccnz .LBB0_647
	s_andn2_b64 vcc, exec, s[26:27]
	s_cbranch_vccnz .LBB0_646
	v_or_b32_e32 v10, s19, v140
	v_mov_b32_e32 v11, v1
	v_mov_b32_e32 v24, v1
	v_mov_b32_e32 v25, v1
	v_add_f32_e32 v10, v6, v224
	v_add_f32_e32 v14, v2, v228
	v_add_f32_e32 v11, v7, v225
	v_add_f32_e32 v15, v3, v229
	v_mul_f32_e32 v10, 0xbfb8aa3b, v10
	v_mul_f32_e32 v14, 0xbfb8aa3b, v14
	v_mul_f32_e32 v11, 0xbfb8aa3b, v11
	v_mul_f32_e32 v15, 0xbfb8aa3b, v15
	v_exp_f32_e32 v10, v10
	v_exp_f32_e32 v14, v14
	v_exp_f32_e32 v11, v11
	v_exp_f32_e32 v15, v15
	v_add_f32_e32 v12, v8, v226
	v_add_f32_e32 v16, v4, v230
	v_add_f32_e32 v13, v9, v227
	v_add_f32_e32 v17, v5, v231
	v_mul_f32_e32 v12, 0xbfb8aa3b, v12
	v_mul_f32_e32 v16, 0xbfb8aa3b, v16
	v_mul_f32_e32 v13, 0xbfb8aa3b, v13
	v_mul_f32_e32 v17, 0xbfb8aa3b, v17
	v_exp_f32_e32 v12, v12
	v_exp_f32_e32 v16, v16
	v_exp_f32_e32 v13, v13
	v_exp_f32_e32 v17, v17
	v_add_f32_e32 v10, 1.0, v10
	v_add_f32_e32 v14, 1.0, v14
	v_add_f32_e32 v11, 1.0, v11
	v_add_f32_e32 v15, 1.0, v15
	v_rcp_f32_e32 v10, v10
	v_rcp_f32_e32 v14, v14
	v_rcp_f32_e32 v11, v11
	v_rcp_f32_e32 v15, v15
	v_add_f32_e32 v12, 1.0, v12
	v_add_f32_e32 v16, 1.0, v16
	v_add_f32_e32 v13, 1.0, v13
	v_add_f32_e32 v17, 1.0, v17
	v_rcp_f32_e32 v12, v12
	v_rcp_f32_e32 v16, v16
	v_rcp_f32_e32 v13, v13
	v_rcp_f32_e32 v17, v17
	v_cvt_pk_fp8_f32 v24, v10, v11
	v_cvt_pk_fp8_f32 v25, v14, v15
	v_lshl_add_u64 v[10:11], s[54:55], 0, v[0:1]
	v_cvt_pk_fp8_f32 v24, v12, v13 op_sel:[0, 0, 1]
	v_cvt_pk_fp8_f32 v25, v16, v17 op_sel:[0, 0, 1]
	v_add_u32_e32 v12, s19, v138
	v_mov_b32_e32 v13, v1
	v_lshl_add_u64 v[10:11], v[10:11], 0, v[12:13]
	global_store_dwordx2 v[10:11], v[24:25], off offset:128

; #define EGAS __attribute__((address_space(1)))
;     __device__ __forceinline__ void operator()(const f32x4 (&acc)[2][2][4][2], const Unit& u, int wr, int wc, int fr, int fq) const {
;     ...
;                         if (pn < 12) {
;                             rope8(v0, v1, WSF(WS_ROPEA) + (row * 64 + (cw >> 1)) * 2);
;                             EGAS bf16_t* O = pn < 6 ? WSB(WS_QA) : WSB(WS_KA); const int c = (pn < 6 ? pn : pn - 6) * 256 + ct;
;                             st8(O + row * WA + c, v0, v1);
.LBB0_656:
	s_add_u32 s26, s8, s17
	s_addc_u32 s27, s9, 0
	s_ashr_i32 s25, s24, 31
	v_pk_mul_f32 v[22:23], v[6:7], v[240:241]
	v_pk_mul_f32 v[6:7], v[6:7], v[240:241] op_sel:[1,0] op_sel_hi:[0,1]
	v_pk_mul_f32 v[20:21], v[8:9], v[242:243]
	v_add_f32_e32 v14, v6, v7
	v_pk_mul_f32 v[6:7], v[8:9], v[242:243] op_sel:[1,0] op_sel_hi:[0,1]
	v_pk_mul_f32 v[8:9], v[2:3], v[244:245]
	v_pk_mul_f32 v[2:3], v[2:3], v[244:245] op_sel:[1,0] op_sel_hi:[0,1]
	v_sub_f32_e32 v8, v8, v9
	v_add_f32_e32 v9, v2, v3
	v_pk_mul_f32 v[2:3], v[4:5], v[246:247] op_sel:[1,0] op_sel_hi:[0,1]
	v_add_f32_e32 v16, v6, v7
	v_pk_mul_f32 v[6:7], v[4:5], v[246:247]
	v_add_f32_e32 v11, v2, v3
	v_lshl_add_u64 v[2:3], v[18:19], 1, s[26:27]
	v_lshl_add_u64 v[4:5], s[24:25], 0, v[138:139]
	v_sub_f32_e32 v10, v6, v7
	v_lshl_add_u64 v[6:7], v[4:5], 1, v[2:3]
	v_sub_f32_e32 v0, v22, v23
	v_sub_f32_e32 v15, v20, v21
	v_cvt_pk_bf16_f32 v2, v0, v14
	v_cvt_pk_bf16_f32 v3, v15, v16
	v_cvt_pk_bf16_f32 v4, v8, v9
	v_cvt_pk_bf16_f32 v5, v10, v11
	global_store_dwordx4 v[6:7], v[2:5], off offset:256
	s_andn2_b64 vcc, exec, s[40:41]
	s_mov_b64 s[24:25], -1
	s_cbranch_vccnz .LBB0_329

; #define EGAS __attribute__((address_space(1)))
;     __device__ __forceinline__ void operator()(const f32x4 (&acc)[2][2][4][2], const Unit& u, int wr, int wc, int fr, int fq) const {
;     ...
;         if constexpr (MODE == EP_IN || MODE == EP_U) {
;             const EGAS float* rsp = WSF(WS_RSTD) + row0;
; #pragma unroll
;             for (int ai = 0; ai < 2; ++ai)
; #pragma unroll
;                 for (int m = 0; m < 4; ++m) rs[ai][m] = rsp[ai * HALF + m * 16];
;         }
;     ...
;                     if constexpr (MODE == EP_IN) {
;                         if (pn < 12) {
;                             rope8(v0, v1, WSF(WS_ROPEA) + (row * 64 + (cw >> 1)) * 2);
;                             EGAS bf16_t* O = pn < 6 ? WSB(WS_QA) : WSB(WS_KA); const int c = (pn < 6 ? pn : pn - 6) * 256 + ct;
;                             st8(O + row * WA + c, v0, v1);
;                         } else if (pn < 18) { st8(WSB(WS_VA) + row * WA + (pn - 12) * 256 + ct, v0, v1);
;                         } else if (pn < 20) { st8(WSB(WS_QL) + row * QLORA + (pn - 18) * 256 + ct, v0, v1);
;                         } else if (pn < 22) { st8(WSB(WS_KVL) + row * KVLORA + (pn - 20) * 256 + ct, v0, v1);
;                         } else if (pn < 38) {
;                             const int gc = (pn - 22) * 256 + ct; const EGAS float* bg = (const EGAS float*)p.f0; const f32x4 b0 = *(const EGAS f32x4*)(bg + gc), b1 = *(const EGAS f32x4*)(bg + gc + 4);
.LBB0_676:
	v_lshl_add_u32 v150, s26, 8, v141
	v_ashrrev_i32_e32 v151, 31, v150
	v_lshl_add_u64 v[148:149], v[150:151], 2, s[50:51]
	global_load_dword v176, v[148:149], off
	global_load_dword v162, v[148:149], off offset:64
	global_load_dword v160, v[148:149], off offset:128
	global_load_dword v158, v[148:149], off offset:192
	global_load_dword v156, v[148:149], off offset:512
	global_load_dword v154, v[148:149], off offset:576
	global_load_dword v152, v[148:149], off offset:640
	s_nop 0
	global_load_dword v148, v[148:149], off offset:704
	s_cmp_gt_i32 s24, 11
	s_cselect_b64 s[42:43], -1, 0
	s_cmp_gt_u32 s24, 17
	s_cselect_b64 s[64:65], -1, 0
	s_cmp_gt_u32 s24, 19
	s_cselect_b64 s[30:31], -1, 0
	s_cmp_gt_u32 s24, 21
	s_cselect_b64 s[28:29], -1, 0
	s_cmp_lt_u32 s24, 38
	s_cselect_b64 s[26:27], -1, 0
	s_cmp_gt_u32 s24, 37
	s_cselect_b64 s[34:35], -1, 0
	s_lshl_b32 s74, s24, 8
	s_movk_i32 s17, 0x600
	s_add_i32 s19, s74, 0xffffea00
	s_add_i32 s25, s74, 0xfffffa00
	v_mul_lo_u32 v164, v150, s17
	s_cmp_lt_i32 s24, 6
	s_mov_b32 s17, 0xd200000
	v_mov_b32_e32 v175, v1
	v_mov_b32_e32 v165, v1
	s_mov_b64 s[36:37], -1
	v_lshlrev_b32_e32 v0, 12, v150
	v_lshlrev_b32_e32 v174, 9, v150
	s_cselect_b32 s17, s17, 0x10200000
	s_cselect_b32 s24, s74, s25
	s_and_b64 vcc, s[28:29], s[26:27]
	s_cbranch_vccz .Lin_nogate_1
	v_or_b32_e32 v232, s19, v138
	v_mov_b32_e32 v233, v1
	v_lshl_add_u64 v[232:233], v[232:233], 2, s[10:11]
	global_load_dwordx4 v[216:219], v[232:233], off
	global_load_dwordx4 v[220:223], v[232:233], off offset:16
	global_load_dwordx4 v[224:227], v[232:233], off offset:512
	global_load_dwordx4 v[228:231], v[232:233], off offset:528

; #define EGAS __attribute__((address_space(1)))
; __device__ __forceinline__ float sigm(float x) { return __builtin_amdgcn_rcpf(1.f + __expf(-x)); }
;     __device__ __forceinline__ void operator()(const f32x4 (&acc)[2][2][4][2], const Unit& u, int wr, int wc, int fr, int fq) const {
;     ...
;                 for (int bj = 0; bj < 2; ++bj) {
;                     f32x4 v0 = acc[ai][bj][m][0], v1 = acc[ai][bj][m][1];
;                     if constexpr (MODE == EP_IN || MODE == EP_U) { v0 = v0 * rs[ai][m]; v1 = v1 * rs[ai][m]; }
;                     const int ct = bj * HALF + cw;
;                     if constexpr (MODE == EP_IN) {
;                         if (pn < 12) {
;                             rope8(v0, v1, WSF(WS_ROPEA) + (row * 64 + (cw >> 1)) * 2);
;                             EGAS bf16_t* O = pn < 6 ? WSB(WS_QA) : WSB(WS_KA); const int c = (pn < 6 ? pn : pn - 6) * 256 + ct;
;                             st8(O + row * WA + c, v0, v1);
;                         } else if (pn < 18) { st8(WSB(WS_VA) + row * WA + (pn - 12) * 256 + ct, v0, v1);
;                         } else if (pn < 20) { st8(WSB(WS_QL) + row * QLORA + (pn - 18) * 256 + ct, v0, v1);
;                         } else if (pn < 22) { st8(WSB(WS_KVL) + row * KVLORA + (pn - 20) * 256 + ct, v0, v1);
;                         } else if (pn < 38) {
;                             const int gc = (pn - 22) * 256 + ct; const EGAS float* bg = (const EGAS float*)p.f0; const f32x4 b0 = *(const EGAS f32x4*)(bg + gc), b1 = *(const EGAS f32x4*)(bg + gc + 4);
; #pragma unroll
;                             for (int e = 0; e < 4; ++e) { v0[e] = sigm(v0[e] + b0[e]); v1[e] = sigm(v1[e] + b1[e]); }
;                             st8f8(WS8(WS_GATES) + row * 4096 + gc, v0, v1);
;                         } else {
;                             if (bj == 0 && wc < 2) { rope8(v0, v1, WSF(WS_ROPEB) + (row * 32 + (cw >> 1)) * 2); st8f8(WS8(WS_KPE) + row * 64 + cw, v0, v1); }
.Lin_norope_1:
	s_and_b64 vcc, exec, s[42:43]
	s_waitcnt vmcnt(0)
	v_pk_mul_f32 v[128:129], v[128:129], v[176:177] op_sel_hi:[1,0]
	v_pk_mul_f32 v[178:179], v[126:127], v[176:177] op_sel_hi:[1,0]
	v_pk_mul_f32 v[124:125], v[124:125], v[176:177] op_sel_hi:[1,0]
	v_pk_mul_f32 v[126:127], v[122:123], v[176:177] op_sel_hi:[1,0]
	s_cbranch_vccz .LBB0_696
	s_and_b64 vcc, exec, s[64:65]
	s_cbranch_vccz .LBB0_693
	s_and_b64 vcc, exec, s[30:31]
	s_cbranch_vccz .LBB0_690
	s_and_b64 vcc, exec, s[28:29]
	s_cbranch_vccz .LBB0_687
	s_and_b64 vcc, exec, s[34:35]
	s_cbranch_vccz .LBB0_684
	s_andn2_b64 vcc, exec, s[14:15]
	s_cbranch_vccnz .LBB0_683
	v_lshlrev_b32_e32 v122, 6, v150
	v_readlane_b32 s36, v255, 53
	v_or_b32_e32 v180, v122, v138
	v_mov_b32_e32 v181, v1
	v_readlane_b32 s37, v255, 54
	v_mov_b32_e32 v123, v1
	v_lshl_add_u64 v[122:123], v[142:143], 0, v[122:123]
	v_lshl_add_u64 v[180:181], v[180:181], 2, s[36:37]
	global_load_dwordx4 v[184:187], v[180:181], off offset:16
	global_load_dwordx4 v[208:211], v[180:181], off
	s_waitcnt vmcnt(0)
	v_pk_mul_f32 v[180:181], v[128:129], v[210:211]
	s_nop 0
	v_sub_f32_e32 v153, v180, v181
	v_pk_mul_f32 v[180:181], v[128:129], v[210:211] op_sel:[1,0] op_sel_hi:[0,1]
	v_pk_mul_f32 v[212:213], v[178:179], v[208:209]
	v_pk_mul_f32 v[208:209], v[178:179], v[208:209] op_sel:[1,0] op_sel_hi:[0,1]
	v_add_f32_e32 v155, v180, v181
	v_pk_mul_f32 v[180:181], v[124:125], v[186:187]
	v_add_f32_e32 v151, v208, v209
	v_pk_mul_f32 v[208:209], v[126:127], v[184:185]
	v_pk_mul_f32 v[184:185], v[126:127], v[184:185] op_sel:[1,0] op_sel_hi:[0,1]
	v_sub_f32_e32 v161, v180, v181
	v_pk_mul_f32 v[180:181], v[124:125], v[186:187] op_sel:[1,0] op_sel_hi:[0,1]
	v_sub_f32_e32 v149, v212, v213
	v_sub_f32_e32 v157, v208, v209
	v_add_f32_e32 v159, v184, v185
	v_add_f32_e32 v163, v180, v181
	v_mov_b32_e32 v180, v1
	v_mov_b32_e32 v181, v1
	v_cvt_pk_fp8_f32 v180, v149, v151
	v_cvt_pk_fp8_f32 v181, v157, v159
	v_cvt_pk_fp8_f32 v180, v153, v155 op_sel:[0,0,1]
	v_cvt_pk_fp8_f32 v181, v161, v163 op_sel:[0,0,1]
	global_store_dwordx2 v[122:123], v[180:181], off

; #define EGAS __attribute__((address_space(1)))
; __device__ __forceinline__ float sigm(float x) { return __builtin_amdgcn_rcpf(1.f + __expf(-x)); }
; __device__ __forceinline__ void st8f8(EGAS unsigned char* dst, f32x4 v0, f32x4 v1) {
;     int w0 = __builtin_amdgcn_cvt_pk_fp8_f32(v0[0], v0[1], 0, false); w0 = __builtin_amdgcn_cvt_pk_fp8_f32(v0[2], v0[3], w0, true);
;     int w1 = __builtin_amdgcn_cvt_pk_fp8_f32(v1[0], v1[1], 0, false); w1 = __builtin_amdgcn_cvt_pk_fp8_f32(v1[2], v1[3], w1, true);
;     *(EGAS u32x2e*)dst = (u32x2e){(unsigned)w0, (unsigned)w1}; }
;     __device__ __forceinline__ void operator()(const f32x4 (&acc)[2][2][4][2], const Unit& u, int wr, int wc, int fr, int fq) const {
;     ...
;                         } else if (pn < 38) {
;                             const int gc = (pn - 22) * 256 + ct; const EGAS float* bg = (const EGAS float*)p.f0; const f32x4 b0 = *(const EGAS f32x4*)(bg + gc), b1 = *(const EGAS f32x4*)(bg + gc + 4);
; #pragma unroll
;                             for (int e = 0; e < 4; ++e) { v0[e] = sigm(v0[e] + b0[e]); v1[e] = sigm(v1[e] + b1[e]); }
;                             st8f8(WS8(WS_GATES) + row * 4096 + gc, v0, v1);
.LBB0_684:
	s_andn2_b64 vcc, exec, s[36:37]
	s_cbranch_vccnz .LBB0_686
	v_or_b32_e32 v122, s19, v138
	v_mov_b32_e32 v123, v1
	v_mov_b32_e32 v180, v1
	v_mov_b32_e32 v181, v1
	v_add_f32_e32 v149, v178, v216
	v_add_f32_e32 v151, v126, v220
	v_add_f32_e32 v153, v179, v217
	v_add_f32_e32 v155, v127, v221
	v_mul_f32_e32 v149, 0xbfb8aa3b, v149
	v_mul_f32_e32 v151, 0xbfb8aa3b, v151
	v_mul_f32_e32 v153, 0xbfb8aa3b, v153
	v_mul_f32_e32 v155, 0xbfb8aa3b, v155
	v_exp_f32_e32 v149, v149
	v_exp_f32_e32 v151, v151
	v_exp_f32_e32 v153, v153
	v_exp_f32_e32 v155, v155
	v_add_f32_e32 v157, v128, v218
	v_add_f32_e32 v159, v124, v222
	v_add_f32_e32 v161, v129, v219
	v_add_f32_e32 v163, v125, v223
	v_mul_f32_e32 v157, 0xbfb8aa3b, v157
	v_mul_f32_e32 v159, 0xbfb8aa3b, v159
	v_mul_f32_e32 v161, 0xbfb8aa3b, v161
	v_mul_f32_e32 v163, 0xbfb8aa3b, v163
	v_exp_f32_e32 v157, v157
	v_exp_f32_e32 v159, v159
	v_exp_f32_e32 v161, v161
	v_exp_f32_e32 v163, v163
	v_add_f32_e32 v149, 1.0, v149
	v_add_f32_e32 v151, 1.0, v151
	v_add_f32_e32 v153, 1.0, v153
	v_add_f32_e32 v155, 1.0, v155
	v_rcp_f32_e32 v149, v149
	v_rcp_f32_e32 v151, v151
	v_rcp_f32_e32 v153, v153
	v_rcp_f32_e32 v155, v155
	v_add_f32_e32 v157, 1.0, v157
	v_add_f32_e32 v159, 1.0, v159
	v_add_f32_e32 v161, 1.0, v161
	v_add_f32_e32 v163, 1.0, v163
	v_rcp_f32_e32 v157, v157
	v_rcp_f32_e32 v159, v159
	v_rcp_f32_e32 v161, v161
	v_rcp_f32_e32 v163, v163
	v_cvt_pk_fp8_f32 v180, v149, v153
	v_cvt_pk_fp8_f32 v181, v151, v155
	v_lshl_add_u64 v[184:185], s[54:55], 0, v[0:1]
	v_lshl_add_u64 v[122:123], v[184:185], 0, v[122:123]
	v_cvt_pk_fp8_f32 v180, v157, v161 op_sel:[0, 0, 1]
	v_cvt_pk_fp8_f32 v181, v159, v163 op_sel:[0, 0, 1]
	global_store_dwordx2 v[122:123], v[180:181], off

; #define EGAS __attribute__((address_space(1)))
; __device__ __forceinline__ float sigm(float x) { return __builtin_amdgcn_rcpf(1.f + __expf(-x)); }
;     __device__ __forceinline__ void operator()(const f32x4 (&acc)[2][2][4][2], const Unit& u, int wr, int wc, int fr, int fq) const {
;     ...
;                 for (int bj = 0; bj < 2; ++bj) {
;                     f32x4 v0 = acc[ai][bj][m][0], v1 = acc[ai][bj][m][1];
;                     if constexpr (MODE == EP_IN || MODE == EP_U) { v0 = v0 * rs[ai][m]; v1 = v1 * rs[ai][m]; }
;                     const int ct = bj * HALF + cw;
;                     if constexpr (MODE == EP_IN) {
;                         if (pn < 12) {
;                             rope8(v0, v1, WSF(WS_ROPEA) + (row * 64 + (cw >> 1)) * 2);
;                             EGAS bf16_t* O = pn < 6 ? WSB(WS_QA) : WSB(WS_KA); const int c = (pn < 6 ? pn : pn - 6) * 256 + ct;
;                             st8(O + row * WA + c, v0, v1);
;                         } else if (pn < 18) { st8(WSB(WS_VA) + row * WA + (pn - 12) * 256 + ct, v0, v1);
;                         } else if (pn < 20) { st8(WSB(WS_QL) + row * QLORA + (pn - 18) * 256 + ct, v0, v1);
;                         } else if (pn < 22) { st8(WSB(WS_KVL) + row * KVLORA + (pn - 20) * 256 + ct, v0, v1);
;                         } else if (pn < 38) {
;                             const int gc = (pn - 22) * 256 + ct; const EGAS float* bg = (const EGAS float*)p.f0; const f32x4 b0 = *(const EGAS f32x4*)(bg + gc), b1 = *(const EGAS f32x4*)(bg + gc + 4);
; #pragma unroll
;                             for (int e = 0; e < 4; ++e) { v0[e] = sigm(v0[e] + b0[e]); v1[e] = sigm(v1[e] + b1[e]); }
;                             st8f8(WS8(WS_GATES) + row * 4096 + gc, v0, v1);
.LBB0_696:
	v_lshl_or_b32 v122, v150, 7, v138
	v_mov_b32_e32 v123, v1
	s_andn2_b64 vcc, exec, s[36:37]
	v_lshl_add_u64 v[180:181], v[122:123], 2, s[62:63]
	v_or_b32_e32 v122, s24, v138
	s_cbranch_vccnz .LBB0_698
	s_add_u32 s36, s8, s17
	s_addc_u32 s37, s9, 0
	v_ashrrev_i32_e32 v123, 31, v122
	v_pk_mul_f32 v[212:213], v[128:129], v[218:219]
	v_pk_mul_f32 v[128:129], v[128:129], v[218:219] op_sel:[1,0] op_sel_hi:[0,1]
	v_pk_mul_f32 v[214:215], v[178:179], v[216:217]
	v_pk_mul_f32 v[178:179], v[178:179], v[216:217] op_sel:[1,0] op_sel_hi:[0,1]
	v_add_f32_e32 v155, v128, v129
	v_pk_mul_f32 v[128:129], v[124:125], v[222:223]
	v_pk_mul_f32 v[124:125], v[124:125], v[222:223] op_sel:[1,0] op_sel_hi:[0,1]
	v_add_f32_e32 v151, v178, v179
	v_pk_mul_f32 v[178:179], v[126:127], v[220:221]
	v_pk_mul_f32 v[126:127], v[126:127], v[220:221] op_sel:[1,0] op_sel_hi:[0,1]
	v_add_f32_e32 v159, v124, v125
	v_lshl_add_u64 v[124:125], v[164:165], 1, s[36:37]
	v_add_f32_e32 v126, v126, v127
	v_sub_f32_e32 v127, v128, v129
	v_lshl_add_u64 v[128:129], v[122:123], 1, v[124:125]
	v_sub_f32_e32 v149, v214, v215
	v_sub_f32_e32 v153, v212, v213
	v_sub_f32_e32 v157, v178, v179
	v_cvt_pk_bf16_f32 v124, v149, v151
	v_cvt_pk_bf16_f32 v125, v153, v155
	v_cvt_pk_bf16_f32 v126, v157, v126
	v_cvt_pk_bf16_f32 v127, v127, v159
	global_store_dwordx4 v[128:129], v[124:127], off
.LBB0_698:
	v_cndmask_b32_e64 v123, 0, 1, s[42:43]
	v_mov_b32_e32 v177, v176
	v_mov_b32_e32 v124, v176
	v_mov_b32_e32 v125, v176
	v_cmp_ne_u32_e64 s[44:45], 1, v123
	v_cndmask_b32_e64 v123, 0, 1, s[64:65]
	v_pk_mul_f32 v[120:121], v[120:121], v[124:125]
	v_pk_mul_f32 v[118:119], v[118:119], v[176:177]
	v_pk_mul_f32 v[116:117], v[116:117], v[124:125]
	v_pk_mul_f32 v[114:115], v[114:115], v[176:177]
	s_mov_b64 s[36:37], -1
	s_andn2_b64 vcc, exec, s[42:43]
	v_cmp_ne_u32_e64 s[42:43], 1, v123
	s_cbranch_vccnz .LBB0_714
	s_and_b64 vcc, exec, s[42:43]
	s_cbranch_vccnz .LBB0_711
	s_andn2_b64 vcc, exec, s[30:31]
	s_cbranch_vccnz .LBB0_708
	s_andn2_b64 vcc, exec, s[28:29]
	s_cbranch_vccnz .LBB0_705
	s_andn2_b64 vcc, exec, s[26:27]
	s_cbranch_vccnz .LBB0_704
	v_add_u32_e32 v128, s19, v138
	v_mov_b32_e32 v129, v1
	v_mov_b32_e32 v184, v1
	v_mov_b32_e32 v185, v1
	v_add_f32_e32 v123, v118, v224
	v_add_f32_e32 v124, v114, v228
	v_add_f32_e32 v125, v119, v225
	v_add_f32_e32 v149, v115, v229
	v_mul_f32_e32 v123, 0xbfb8aa3b, v123
	v_mul_f32_e32 v124, 0xbfb8aa3b, v124
	v_mul_f32_e32 v125, 0xbfb8aa3b, v125
	v_mul_f32_e32 v149, 0xbfb8aa3b, v149
	v_exp_f32_e32 v123, v123
	v_exp_f32_e32 v124, v124
	v_exp_f32_e32 v125, v125
	v_exp_f32_e32 v149, v149
	v_add_f32_e32 v126, v120, v226
	v_add_f32_e32 v151, v116, v230
	v_add_f32_e32 v127, v121, v227
	v_add_f32_e32 v153, v117, v231
	v_mul_f32_e32 v126, 0xbfb8aa3b, v126
	v_mul_f32_e32 v151, 0xbfb8aa3b, v151
	v_mul_f32_e32 v127, 0xbfb8aa3b, v127
	v_mul_f32_e32 v153, 0xbfb8aa3b, v153
	v_exp_f32_e32 v126, v126
	v_exp_f32_e32 v151, v151
	v_exp_f32_e32 v127, v127
	v_exp_f32_e32 v153, v153
	v_add_f32_e32 v123, 1.0, v123
	v_add_f32_e32 v124, 1.0, v124
	v_add_f32_e32 v125, 1.0, v125
	v_add_f32_e32 v149, 1.0, v149
	v_rcp_f32_e32 v123, v123
	v_rcp_f32_e32 v124, v124
	v_rcp_f32_e32 v125, v125
	v_rcp_f32_e32 v149, v149
	v_add_f32_e32 v126, 1.0, v126
	v_add_f32_e32 v151, 1.0, v151
	v_add_f32_e32 v127, 1.0, v127
	v_add_f32_e32 v153, 1.0, v153
	v_rcp_f32_e32 v126, v126
	v_rcp_f32_e32 v151, v151
	v_rcp_f32_e32 v127, v127
	v_rcp_f32_e32 v153, v153
	v_cvt_pk_fp8_f32 v184, v123, v125
	v_cvt_pk_fp8_f32 v185, v124, v149
	v_lshl_add_u64 v[124:125], s[54:55], 0, v[0:1]
	v_lshl_add_u64 v[124:125], v[124:125], 0, v[128:129]
	v_cvt_pk_fp8_f32 v184, v126, v127 op_sel:[0, 0, 1]
	v_cvt_pk_fp8_f32 v185, v151, v153 op_sel:[0, 0, 1]
	global_store_dwordx2 v[124:125], v[184:185], off offset:128

; #define EGAS __attribute__((address_space(1)))
;     __device__ __forceinline__ void operator()(const f32x4 (&acc)[2][2][4][2], const Unit& u, int wr, int wc, int fr, int fq) const {
;     ...
;                         if (pn < 12) {
;                             rope8(v0, v1, WSF(WS_ROPEA) + (row * 64 + (cw >> 1)) * 2);
;                             EGAS bf16_t* O = pn < 6 ? WSB(WS_QA) : WSB(WS_KA); const int c = (pn < 6 ? pn : pn - 6) * 256 + ct;
;                             st8(O + row * WA + c, v0, v1);
.LBB0_714:
	s_andn2_b64 vcc, exec, s[36:37]
	s_cbranch_vccnz .LBB0_716
	s_add_u32 s36, s8, s17
	s_addc_u32 s37, s9, 0
	s_ashr_i32 s25, s24, 31
	v_pk_mul_f32 v[178:179], v[118:119], v[216:217]
	v_pk_mul_f32 v[118:119], v[118:119], v[216:217] op_sel:[1,0] op_sel_hi:[0,1]
	v_pk_mul_f32 v[128:129], v[120:121], v[218:219]
	v_add_f32_e32 v123, v118, v119
	v_pk_mul_f32 v[118:119], v[120:121], v[218:219] op_sel:[1,0] op_sel_hi:[0,1]
	v_pk_mul_f32 v[120:121], v[114:115], v[220:221]
	v_pk_mul_f32 v[114:115], v[114:115], v[220:221] op_sel:[1,0] op_sel_hi:[0,1]
	v_sub_f32_e32 v120, v120, v121
	v_add_f32_e32 v121, v114, v115
	v_pk_mul_f32 v[114:115], v[116:117], v[222:223] op_sel:[1,0] op_sel_hi:[0,1]
	v_sub_f32_e32 v128, v128, v129
	v_add_f32_e32 v129, v118, v119
	v_pk_mul_f32 v[118:119], v[116:117], v[222:223]
	v_add_f32_e32 v125, v114, v115
	v_lshl_add_u64 v[114:115], v[164:165], 1, s[36:37]
	v_lshl_add_u64 v[116:117], s[24:25], 0, v[138:139]
	v_sub_f32_e32 v124, v118, v119
	v_lshl_add_u64 v[118:119], v[116:117], 1, v[114:115]
	v_sub_f32_e32 v0, v178, v179
	v_cvt_pk_bf16_f32 v114, v0, v123
	v_cvt_pk_bf16_f32 v115, v128, v129
	v_cvt_pk_bf16_f32 v116, v120, v121
	v_cvt_pk_bf16_f32 v117, v124, v125
	global_store_dwordx4 v[118:119], v[114:117], off offset:256
	v_add_u32_e32 v249, 0x10000, v248
	global_load_dwordx4 v[216:219], v249, s[62:63]
	global_load_dwordx4 v[220:223], v249, s[62:63] offset:16

; #define EGAS __attribute__((address_space(1)))
; __device__ __forceinline__ float sigm(float x) { return __builtin_amdgcn_rcpf(1.f + __expf(-x)); }
;     __device__ __forceinline__ void operator()(const f32x4 (&acc)[2][2][4][2], const Unit& u, int wr, int wc, int fr, int fq) const {
;     ...
;                 for (int bj = 0; bj < 2; ++bj) {
;                     f32x4 v0 = acc[ai][bj][m][0], v1 = acc[ai][bj][m][1];
;                     if constexpr (MODE == EP_IN || MODE == EP_U) { v0 = v0 * rs[ai][m]; v1 = v1 * rs[ai][m]; }
;                     const int ct = bj * HALF + cw;
;                     if constexpr (MODE == EP_IN) {
;                         if (pn < 12) {
;                             rope8(v0, v1, WSF(WS_ROPEA) + (row * 64 + (cw >> 1)) * 2);
;                             EGAS bf16_t* O = pn < 6 ? WSB(WS_QA) : WSB(WS_KA); const int c = (pn < 6 ? pn : pn - 6) * 256 + ct;
;                             st8(O + row * WA + c, v0, v1);
;                         } else if (pn < 18) { st8(WSB(WS_VA) + row * WA + (pn - 12) * 256 + ct, v0, v1);
;                         } else if (pn < 20) { st8(WSB(WS_QL) + row * QLORA + (pn - 18) * 256 + ct, v0, v1);
;                         } else if (pn < 22) { st8(WSB(WS_KVL) + row * KVLORA + (pn - 20) * 256 + ct, v0, v1);
;                         } else if (pn < 38) {
;                             const int gc = (pn - 22) * 256 + ct; const EGAS float* bg = (const EGAS float*)p.f0; const f32x4 b0 = *(const EGAS f32x4*)(bg + gc), b1 = *(const EGAS f32x4*)(bg + gc + 4);
; #pragma unroll
;                             for (int e = 0; e < 4; ++e) { v0[e] = sigm(v0[e] + b0[e]); v1[e] = sigm(v1[e] + b1[e]); }
;                             st8f8(WS8(WS_GATES) + row * 4096 + gc, v0, v1);
.LBB0_738:
	v_mov_b32_e32 v163, v162
	s_nop 0
	v_mov_b32_e32 v106, v162
	v_mov_b32_e32 v107, v162
	v_pk_mul_f32 v[104:105], v[104:105], v[106:107]
	v_pk_mul_f32 v[102:103], v[102:103], v[162:163]
	v_pk_mul_f32 v[100:101], v[100:101], v[106:107]
	v_pk_mul_f32 v[98:99], v[98:99], v[162:163]
	s_and_b64 vcc, exec, s[44:45]
	s_mov_b64 s[36:37], -1
	s_cbranch_vccnz .LBB0_754
	s_and_b64 vcc, exec, s[42:43]
	s_cbranch_vccnz .LBB0_751
	s_andn2_b64 vcc, exec, s[30:31]
	s_cbranch_vccnz .LBB0_748
	s_andn2_b64 vcc, exec, s[28:29]
	s_cbranch_vccnz .LBB0_745
	s_andn2_b64 vcc, exec, s[26:27]
	s_cbranch_vccnz .LBB0_744
	v_add_u32_e32 v120, s19, v138
	v_mov_b32_e32 v121, v1
	v_mov_b32_e32 v124, v1
	v_mov_b32_e32 v125, v1
	v_add_f32_e32 v106, v102, v224
	v_add_f32_e32 v110, v98, v228
	v_add_f32_e32 v107, v103, v225
	v_add_f32_e32 v111, v99, v229
	v_mul_f32_e32 v106, 0xbfb8aa3b, v106
	v_mul_f32_e32 v110, 0xbfb8aa3b, v110
	v_mul_f32_e32 v107, 0xbfb8aa3b, v107
	v_mul_f32_e32 v111, 0xbfb8aa3b, v111
	v_exp_f32_e32 v106, v106
	v_exp_f32_e32 v110, v110
	v_exp_f32_e32 v107, v107
	v_exp_f32_e32 v111, v111
	v_add_f32_e32 v108, v104, v226
	v_add_f32_e32 v112, v100, v230
	v_add_f32_e32 v109, v105, v227
	v_add_f32_e32 v113, v101, v231
	v_mul_f32_e32 v108, 0xbfb8aa3b, v108
	v_mul_f32_e32 v112, 0xbfb8aa3b, v112
	v_mul_f32_e32 v109, 0xbfb8aa3b, v109
	v_mul_f32_e32 v113, 0xbfb8aa3b, v113
	v_exp_f32_e32 v108, v108
	v_exp_f32_e32 v112, v112
	v_exp_f32_e32 v109, v109
	v_exp_f32_e32 v113, v113
	v_add_f32_e32 v106, 1.0, v106
	v_add_f32_e32 v110, 1.0, v110
	v_add_f32_e32 v107, 1.0, v107
	v_add_f32_e32 v111, 1.0, v111
	v_rcp_f32_e32 v106, v106
	v_rcp_f32_e32 v110, v110
	v_rcp_f32_e32 v107, v107
	v_rcp_f32_e32 v111, v111
	v_add_f32_e32 v108, 1.0, v108
	v_add_f32_e32 v112, 1.0, v112
	v_add_f32_e32 v109, 1.0, v109
	v_add_f32_e32 v113, 1.0, v113
	v_rcp_f32_e32 v108, v108
	v_rcp_f32_e32 v112, v112
	v_rcp_f32_e32 v109, v109
	v_rcp_f32_e32 v113, v113
	v_cvt_pk_fp8_f32 v124, v106, v107
	v_cvt_pk_fp8_f32 v125, v110, v111
	v_lshl_add_u64 v[106:107], s[54:55], 0, v[0:1]
	v_lshl_add_u64 v[106:107], v[106:107], 0, v[120:121]
	v_cvt_pk_fp8_f32 v124, v108, v109 op_sel:[0, 0, 1]
	v_cvt_pk_fp8_f32 v125, v112, v113 op_sel:[0, 0, 1]
	global_store_dwordx2 v[106:107], v[124:125], off offset:128

; #define EGAS __attribute__((address_space(1)))
; __device__ __forceinline__ float sigm(float x) { return __builtin_amdgcn_rcpf(1.f + __expf(-x)); }
;     __device__ __forceinline__ void operator()(const f32x4 (&acc)[2][2][4][2], const Unit& u, int wr, int wc, int fr, int fq) const {
;     ...
;                 for (int bj = 0; bj < 2; ++bj) {
;                     f32x4 v0 = acc[ai][bj][m][0], v1 = acc[ai][bj][m][1];
;                     if constexpr (MODE == EP_IN || MODE == EP_U) { v0 = v0 * rs[ai][m]; v1 = v1 * rs[ai][m]; }
;                     const int ct = bj * HALF + cw;
;                     if constexpr (MODE == EP_IN) {
;                         if (pn < 12) {
;                             rope8(v0, v1, WSF(WS_ROPEA) + (row * 64 + (cw >> 1)) * 2);
;                             EGAS bf16_t* O = pn < 6 ? WSB(WS_QA) : WSB(WS_KA); const int c = (pn < 6 ? pn : pn - 6) * 256 + ct;
;                             st8(O + row * WA + c, v0, v1);
;                         } else if (pn < 18) { st8(WSB(WS_VA) + row * WA + (pn - 12) * 256 + ct, v0, v1);
;                         } else if (pn < 20) { st8(WSB(WS_QL) + row * QLORA + (pn - 18) * 256 + ct, v0, v1);
;                         } else if (pn < 22) { st8(WSB(WS_KVL) + row * KVLORA + (pn - 20) * 256 + ct, v0, v1);
;                         } else if (pn < 38) {
;                             const int gc = (pn - 22) * 256 + ct; const EGAS float* bg = (const EGAS float*)p.f0; const f32x4 b0 = *(const EGAS f32x4*)(bg + gc), b1 = *(const EGAS f32x4*)(bg + gc + 4);
; #pragma unroll
;                             for (int e = 0; e < 4; ++e) { v0[e] = sigm(v0[e] + b0[e]); v1[e] = sigm(v1[e] + b1[e]); }
;                             st8f8(WS8(WS_GATES) + row * 4096 + gc, v0, v1);
.LBB0_778:
	v_mov_b32_e32 v161, v160
	s_nop 0
	v_mov_b32_e32 v90, v160
	v_mov_b32_e32 v91, v160
	v_pk_mul_f32 v[88:89], v[88:89], v[90:91]
	v_pk_mul_f32 v[86:87], v[86:87], v[160:161]
	v_pk_mul_f32 v[84:85], v[84:85], v[90:91]
	v_pk_mul_f32 v[82:83], v[82:83], v[160:161]
	s_and_b64 vcc, exec, s[44:45]
	s_mov_b64 s[36:37], -1
	s_cbranch_vccnz .LBB0_794
	s_and_b64 vcc, exec, s[42:43]
	s_cbranch_vccnz .LBB0_791
	s_andn2_b64 vcc, exec, s[30:31]
	s_cbranch_vccnz .LBB0_788
	s_andn2_b64 vcc, exec, s[28:29]
	s_cbranch_vccnz .LBB0_785
	s_andn2_b64 vcc, exec, s[26:27]
	s_cbranch_vccnz .LBB0_784
	v_add_u32_e32 v104, s19, v138
	v_mov_b32_e32 v105, v1
	v_mov_b32_e32 v106, v1
	v_mov_b32_e32 v107, v1
	v_add_f32_e32 v90, v86, v224
	v_add_f32_e32 v94, v82, v228
	v_add_f32_e32 v91, v87, v225
	v_add_f32_e32 v95, v83, v229
	v_mul_f32_e32 v90, 0xbfb8aa3b, v90
	v_mul_f32_e32 v94, 0xbfb8aa3b, v94
	v_mul_f32_e32 v91, 0xbfb8aa3b, v91
	v_mul_f32_e32 v95, 0xbfb8aa3b, v95
	v_exp_f32_e32 v90, v90
	v_exp_f32_e32 v94, v94
	v_exp_f32_e32 v91, v91
	v_exp_f32_e32 v95, v95
	v_add_f32_e32 v92, v88, v226
	v_add_f32_e32 v96, v84, v230
	v_add_f32_e32 v93, v89, v227
	v_add_f32_e32 v97, v85, v231
	v_mul_f32_e32 v92, 0xbfb8aa3b, v92
	v_mul_f32_e32 v96, 0xbfb8aa3b, v96
	v_mul_f32_e32 v93, 0xbfb8aa3b, v93
	v_mul_f32_e32 v97, 0xbfb8aa3b, v97
	v_exp_f32_e32 v92, v92
	v_exp_f32_e32 v96, v96
	v_exp_f32_e32 v93, v93
	v_exp_f32_e32 v97, v97
	v_add_f32_e32 v90, 1.0, v90
	v_add_f32_e32 v94, 1.0, v94
	v_add_f32_e32 v91, 1.0, v91
	v_add_f32_e32 v95, 1.0, v95
	v_rcp_f32_e32 v90, v90
	v_rcp_f32_e32 v94, v94
	v_rcp_f32_e32 v91, v91
	v_rcp_f32_e32 v95, v95
	v_add_f32_e32 v92, 1.0, v92
	v_add_f32_e32 v96, 1.0, v96
	v_add_f32_e32 v93, 1.0, v93
	v_add_f32_e32 v97, 1.0, v97
	v_rcp_f32_e32 v92, v92
	v_rcp_f32_e32 v96, v96
	v_rcp_f32_e32 v93, v93
	v_rcp_f32_e32 v97, v97
	v_cvt_pk_fp8_f32 v106, v90, v91
	v_cvt_pk_fp8_f32 v107, v94, v95
	v_lshl_add_u64 v[90:91], s[54:55], 0, v[0:1]
	v_lshl_add_u64 v[90:91], v[90:91], 0, v[104:105]
	v_cvt_pk_fp8_f32 v106, v92, v93 op_sel:[0, 0, 1]
	v_cvt_pk_fp8_f32 v107, v96, v97 op_sel:[0, 0, 1]
	global_store_dwordx2 v[90:91], v[106:107], off offset:128

; #define EGAS __attribute__((address_space(1)))
; __device__ __forceinline__ float sigm(float x) { return __builtin_amdgcn_rcpf(1.f + __expf(-x)); }
;     __device__ __forceinline__ void operator()(const f32x4 (&acc)[2][2][4][2], const Unit& u, int wr, int wc, int fr, int fq) const {
;     ...
;                 for (int bj = 0; bj < 2; ++bj) {
;                     f32x4 v0 = acc[ai][bj][m][0], v1 = acc[ai][bj][m][1];
;                     if constexpr (MODE == EP_IN || MODE == EP_U) { v0 = v0 * rs[ai][m]; v1 = v1 * rs[ai][m]; }
;                     const int ct = bj * HALF + cw;
;                     if constexpr (MODE == EP_IN) {
;                         if (pn < 12) {
;                             rope8(v0, v1, WSF(WS_ROPEA) + (row * 64 + (cw >> 1)) * 2);
;                             EGAS bf16_t* O = pn < 6 ? WSB(WS_QA) : WSB(WS_KA); const int c = (pn < 6 ? pn : pn - 6) * 256 + ct;
;                             st8(O + row * WA + c, v0, v1);
;                         } else if (pn < 18) { st8(WSB(WS_VA) + row * WA + (pn - 12) * 256 + ct, v0, v1);
;                         } else if (pn < 20) { st8(WSB(WS_QL) + row * QLORA + (pn - 18) * 256 + ct, v0, v1);
;                         } else if (pn < 22) { st8(WSB(WS_KVL) + row * KVLORA + (pn - 20) * 256 + ct, v0, v1);
;                         } else if (pn < 38) {
;                             const int gc = (pn - 22) * 256 + ct; const EGAS float* bg = (const EGAS float*)p.f0; const f32x4 b0 = *(const EGAS f32x4*)(bg + gc), b1 = *(const EGAS f32x4*)(bg + gc + 4);
; #pragma unroll
;                             for (int e = 0; e < 4; ++e) { v0[e] = sigm(v0[e] + b0[e]); v1[e] = sigm(v1[e] + b1[e]); }
;                             st8f8(WS8(WS_GATES) + row * 4096 + gc, v0, v1);
.LBB0_818:
	v_mov_b32_e32 v159, v158
	s_nop 0
	v_mov_b32_e32 v74, v158
	v_mov_b32_e32 v75, v158
	v_pk_mul_f32 v[72:73], v[72:73], v[74:75]
	v_pk_mul_f32 v[70:71], v[70:71], v[158:159]
	v_pk_mul_f32 v[68:69], v[68:69], v[74:75]
	v_pk_mul_f32 v[66:67], v[66:67], v[158:159]
	s_and_b64 vcc, exec, s[44:45]
	s_mov_b64 s[36:37], -1
	s_cbranch_vccnz .LBB0_834
	s_and_b64 vcc, exec, s[42:43]
	s_cbranch_vccnz .LBB0_831
	s_andn2_b64 vcc, exec, s[30:31]
	s_cbranch_vccnz .LBB0_828
	s_andn2_b64 vcc, exec, s[28:29]
	s_cbranch_vccnz .LBB0_825
	s_andn2_b64 vcc, exec, s[26:27]
	s_cbranch_vccnz .LBB0_824
	v_add_u32_e32 v88, s19, v138
	v_mov_b32_e32 v89, v1
	v_mov_b32_e32 v90, v1
	v_mov_b32_e32 v91, v1
	v_add_f32_e32 v74, v70, v224
	v_add_f32_e32 v78, v66, v228
	v_add_f32_e32 v75, v71, v225
	v_add_f32_e32 v79, v67, v229
	v_mul_f32_e32 v74, 0xbfb8aa3b, v74
	v_mul_f32_e32 v78, 0xbfb8aa3b, v78
	v_mul_f32_e32 v75, 0xbfb8aa3b, v75
	v_mul_f32_e32 v79, 0xbfb8aa3b, v79
	v_exp_f32_e32 v74, v74
	v_exp_f32_e32 v78, v78
	v_exp_f32_e32 v75, v75
	v_exp_f32_e32 v79, v79
	v_add_f32_e32 v76, v72, v226
	v_add_f32_e32 v80, v68, v230
	v_add_f32_e32 v77, v73, v227
	v_add_f32_e32 v81, v69, v231
	v_mul_f32_e32 v76, 0xbfb8aa3b, v76
	v_mul_f32_e32 v80, 0xbfb8aa3b, v80
	v_mul_f32_e32 v77, 0xbfb8aa3b, v77
	v_mul_f32_e32 v81, 0xbfb8aa3b, v81
	v_exp_f32_e32 v76, v76
	v_exp_f32_e32 v80, v80
	v_exp_f32_e32 v77, v77
	v_exp_f32_e32 v81, v81
	v_add_f32_e32 v74, 1.0, v74
	v_add_f32_e32 v78, 1.0, v78
	v_add_f32_e32 v75, 1.0, v75
	v_add_f32_e32 v79, 1.0, v79
	v_rcp_f32_e32 v74, v74
	v_rcp_f32_e32 v78, v78
	v_rcp_f32_e32 v75, v75
	v_rcp_f32_e32 v79, v79
	v_add_f32_e32 v76, 1.0, v76
	v_add_f32_e32 v80, 1.0, v80
	v_add_f32_e32 v77, 1.0, v77
	v_add_f32_e32 v81, 1.0, v81
	v_rcp_f32_e32 v76, v76
	v_rcp_f32_e32 v80, v80
	v_rcp_f32_e32 v77, v77
	v_rcp_f32_e32 v81, v81
	v_cvt_pk_fp8_f32 v90, v74, v75
	v_cvt_pk_fp8_f32 v91, v78, v79
	v_lshl_add_u64 v[74:75], s[54:55], 0, v[0:1]
	v_lshl_add_u64 v[74:75], v[74:75], 0, v[88:89]
	v_cvt_pk_fp8_f32 v90, v76, v77 op_sel:[0, 0, 1]
	v_cvt_pk_fp8_f32 v91, v80, v81 op_sel:[0, 0, 1]
	global_store_dwordx2 v[74:75], v[90:91], off offset:128

; #define EGAS __attribute__((address_space(1)))
; __device__ __forceinline__ float sigm(float x) { return __builtin_amdgcn_rcpf(1.f + __expf(-x)); }
;     __device__ __forceinline__ void operator()(const f32x4 (&acc)[2][2][4][2], const Unit& u, int wr, int wc, int fr, int fq) const {
;     ...
;                 for (int bj = 0; bj < 2; ++bj) {
;                     f32x4 v0 = acc[ai][bj][m][0], v1 = acc[ai][bj][m][1];
;                     if constexpr (MODE == EP_IN || MODE == EP_U) { v0 = v0 * rs[ai][m]; v1 = v1 * rs[ai][m]; }
;                     const int ct = bj * HALF + cw;
;                     if constexpr (MODE == EP_IN) {
;                         if (pn < 12) {
;                             rope8(v0, v1, WSF(WS_ROPEA) + (row * 64 + (cw >> 1)) * 2);
;                             EGAS bf16_t* O = pn < 6 ? WSB(WS_QA) : WSB(WS_KA); const int c = (pn < 6 ? pn : pn - 6) * 256 + ct;
;                             st8(O + row * WA + c, v0, v1);
;                         } else if (pn < 18) { st8(WSB(WS_VA) + row * WA + (pn - 12) * 256 + ct, v0, v1);
;                         } else if (pn < 20) { st8(WSB(WS_QL) + row * QLORA + (pn - 18) * 256 + ct, v0, v1);
;                         } else if (pn < 22) { st8(WSB(WS_KVL) + row * KVLORA + (pn - 20) * 256 + ct, v0, v1);
;                         } else if (pn < 38) {
;                             const int gc = (pn - 22) * 256 + ct; const EGAS float* bg = (const EGAS float*)p.f0; const f32x4 b0 = *(const EGAS f32x4*)(bg + gc), b1 = *(const EGAS f32x4*)(bg + gc + 4);
; #pragma unroll
;                             for (int e = 0; e < 4; ++e) { v0[e] = sigm(v0[e] + b0[e]); v1[e] = sigm(v1[e] + b1[e]); }
;                             st8f8(WS8(WS_GATES) + row * 4096 + gc, v0, v1);
.LBB0_858:
	v_mov_b32_e32 v157, v156
	s_nop 0
	v_mov_b32_e32 v58, v156
	v_mov_b32_e32 v59, v156
	v_pk_mul_f32 v[56:57], v[56:57], v[58:59]
	v_pk_mul_f32 v[54:55], v[54:55], v[156:157]
	v_pk_mul_f32 v[52:53], v[52:53], v[58:59]
	v_pk_mul_f32 v[50:51], v[50:51], v[156:157]
	s_and_b64 vcc, exec, s[44:45]
	s_mov_b64 s[36:37], -1
	s_cbranch_vccnz .LBB0_874
	s_and_b64 vcc, exec, s[42:43]
	s_cbranch_vccnz .LBB0_871
	s_andn2_b64 vcc, exec, s[30:31]
	s_cbranch_vccnz .LBB0_868
	s_andn2_b64 vcc, exec, s[28:29]
	s_cbranch_vccnz .LBB0_865
	s_andn2_b64 vcc, exec, s[26:27]
	s_cbranch_vccnz .LBB0_864
	v_add_u32_e32 v72, s19, v138
	v_mov_b32_e32 v73, v1
	v_mov_b32_e32 v74, v1
	v_mov_b32_e32 v75, v1
	v_add_f32_e32 v58, v54, v224
	v_add_f32_e32 v62, v50, v228
	v_add_f32_e32 v59, v55, v225
	v_add_f32_e32 v63, v51, v229
	v_mul_f32_e32 v58, 0xbfb8aa3b, v58
	v_mul_f32_e32 v62, 0xbfb8aa3b, v62
	v_mul_f32_e32 v59, 0xbfb8aa3b, v59
	v_mul_f32_e32 v63, 0xbfb8aa3b, v63
	v_exp_f32_e32 v58, v58
	v_exp_f32_e32 v62, v62
	v_exp_f32_e32 v59, v59
	v_exp_f32_e32 v63, v63
	v_add_f32_e32 v60, v56, v226
	v_add_f32_e32 v64, v52, v230
	v_add_f32_e32 v61, v57, v227
	v_add_f32_e32 v65, v53, v231
	v_mul_f32_e32 v60, 0xbfb8aa3b, v60
	v_mul_f32_e32 v64, 0xbfb8aa3b, v64
	v_mul_f32_e32 v61, 0xbfb8aa3b, v61
	v_mul_f32_e32 v65, 0xbfb8aa3b, v65
	v_exp_f32_e32 v60, v60
	v_exp_f32_e32 v64, v64
	v_exp_f32_e32 v61, v61
	v_exp_f32_e32 v65, v65
	v_add_f32_e32 v58, 1.0, v58
	v_add_f32_e32 v62, 1.0, v62
	v_add_f32_e32 v59, 1.0, v59
	v_add_f32_e32 v63, 1.0, v63
	v_rcp_f32_e32 v58, v58
	v_rcp_f32_e32 v62, v62
	v_rcp_f32_e32 v59, v59
	v_rcp_f32_e32 v63, v63
	v_add_f32_e32 v60, 1.0, v60
	v_add_f32_e32 v64, 1.0, v64
	v_add_f32_e32 v61, 1.0, v61
	v_add_f32_e32 v65, 1.0, v65
	v_rcp_f32_e32 v60, v60
	v_rcp_f32_e32 v64, v64
	v_rcp_f32_e32 v61, v61
	v_rcp_f32_e32 v65, v65
	v_cvt_pk_fp8_f32 v74, v58, v59
	v_cvt_pk_fp8_f32 v75, v62, v63
	v_lshl_add_u64 v[58:59], s[54:55], 0, v[0:1]
	v_lshl_add_u64 v[58:59], v[58:59], 0, v[72:73]
	v_cvt_pk_fp8_f32 v74, v60, v61 op_sel:[0, 0, 1]
	v_cvt_pk_fp8_f32 v75, v64, v65 op_sel:[0, 0, 1]
	global_store_dwordx2 v[58:59], v[74:75], off offset:128

; #define EGAS __attribute__((address_space(1)))
; __device__ __forceinline__ float sigm(float x) { return __builtin_amdgcn_rcpf(1.f + __expf(-x)); }
;     __device__ __forceinline__ void operator()(const f32x4 (&acc)[2][2][4][2], const Unit& u, int wr, int wc, int fr, int fq) const {
;     ...
;                 for (int bj = 0; bj < 2; ++bj) {
;                     f32x4 v0 = acc[ai][bj][m][0], v1 = acc[ai][bj][m][1];
;                     if constexpr (MODE == EP_IN || MODE == EP_U) { v0 = v0 * rs[ai][m]; v1 = v1 * rs[ai][m]; }
;                     const int ct = bj * HALF + cw;
;                     if constexpr (MODE == EP_IN) {
;                         if (pn < 12) {
;                             rope8(v0, v1, WSF(WS_ROPEA) + (row * 64 + (cw >> 1)) * 2);
;                             EGAS bf16_t* O = pn < 6 ? WSB(WS_QA) : WSB(WS_KA); const int c = (pn < 6 ? pn : pn - 6) * 256 + ct;
;                             st8(O + row * WA + c, v0, v1);
;                         } else if (pn < 18) { st8(WSB(WS_VA) + row * WA + (pn - 12) * 256 + ct, v0, v1);
;                         } else if (pn < 20) { st8(WSB(WS_QL) + row * QLORA + (pn - 18) * 256 + ct, v0, v1);
;                         } else if (pn < 22) { st8(WSB(WS_KVL) + row * KVLORA + (pn - 20) * 256 + ct, v0, v1);
;                         } else if (pn < 38) {
;                             const int gc = (pn - 22) * 256 + ct; const EGAS float* bg = (const EGAS float*)p.f0; const f32x4 b0 = *(const EGAS f32x4*)(bg + gc), b1 = *(const EGAS f32x4*)(bg + gc + 4);
; #pragma unroll
;                             for (int e = 0; e < 4; ++e) { v0[e] = sigm(v0[e] + b0[e]); v1[e] = sigm(v1[e] + b1[e]); }
;                             st8f8(WS8(WS_GATES) + row * 4096 + gc, v0, v1);
.LBB0_898:
	v_mov_b32_e32 v155, v154
	s_nop 0
	v_mov_b32_e32 v42, v154
	v_mov_b32_e32 v43, v154
	v_pk_mul_f32 v[40:41], v[40:41], v[42:43]
	v_pk_mul_f32 v[38:39], v[38:39], v[154:155]
	v_pk_mul_f32 v[36:37], v[36:37], v[42:43]
	v_pk_mul_f32 v[34:35], v[34:35], v[154:155]
	s_and_b64 vcc, exec, s[44:45]
	s_mov_b64 s[36:37], -1
	s_cbranch_vccnz .LBB0_914
	s_and_b64 vcc, exec, s[42:43]
	s_cbranch_vccnz .LBB0_911
	s_andn2_b64 vcc, exec, s[30:31]
	s_cbranch_vccnz .LBB0_908
	s_andn2_b64 vcc, exec, s[28:29]
	s_cbranch_vccnz .LBB0_905
	s_andn2_b64 vcc, exec, s[26:27]
	s_cbranch_vccnz .LBB0_904
	v_add_u32_e32 v56, s19, v138
	v_mov_b32_e32 v57, v1
	v_mov_b32_e32 v58, v1
	v_mov_b32_e32 v59, v1
	v_add_f32_e32 v42, v38, v224
	v_add_f32_e32 v46, v34, v228
	v_add_f32_e32 v43, v39, v225
	v_add_f32_e32 v47, v35, v229
	v_mul_f32_e32 v42, 0xbfb8aa3b, v42
	v_mul_f32_e32 v46, 0xbfb8aa3b, v46
	v_mul_f32_e32 v43, 0xbfb8aa3b, v43
	v_mul_f32_e32 v47, 0xbfb8aa3b, v47
	v_exp_f32_e32 v42, v42
	v_exp_f32_e32 v46, v46
	v_exp_f32_e32 v43, v43
	v_exp_f32_e32 v47, v47
	v_add_f32_e32 v44, v40, v226
	v_add_f32_e32 v48, v36, v230
	v_add_f32_e32 v45, v41, v227
	v_add_f32_e32 v49, v37, v231
	v_mul_f32_e32 v44, 0xbfb8aa3b, v44
	v_mul_f32_e32 v48, 0xbfb8aa3b, v48
	v_mul_f32_e32 v45, 0xbfb8aa3b, v45
	v_mul_f32_e32 v49, 0xbfb8aa3b, v49
	v_exp_f32_e32 v44, v44
	v_exp_f32_e32 v48, v48
	v_exp_f32_e32 v45, v45
	v_exp_f32_e32 v49, v49
	v_add_f32_e32 v42, 1.0, v42
	v_add_f32_e32 v46, 1.0, v46
	v_add_f32_e32 v43, 1.0, v43
	v_add_f32_e32 v47, 1.0, v47
	v_rcp_f32_e32 v42, v42
	v_rcp_f32_e32 v46, v46
	v_rcp_f32_e32 v43, v43
	v_rcp_f32_e32 v47, v47
	v_add_f32_e32 v44, 1.0, v44
	v_add_f32_e32 v48, 1.0, v48
	v_add_f32_e32 v45, 1.0, v45
	v_add_f32_e32 v49, 1.0, v49
	v_rcp_f32_e32 v44, v44
	v_rcp_f32_e32 v48, v48
	v_rcp_f32_e32 v45, v45
	v_rcp_f32_e32 v49, v49
	v_cvt_pk_fp8_f32 v58, v42, v43
	v_cvt_pk_fp8_f32 v59, v46, v47
	v_lshl_add_u64 v[42:43], s[54:55], 0, v[0:1]
	v_lshl_add_u64 v[42:43], v[42:43], 0, v[56:57]
	v_cvt_pk_fp8_f32 v58, v44, v45 op_sel:[0, 0, 1]
	v_cvt_pk_fp8_f32 v59, v48, v49 op_sel:[0, 0, 1]
	global_store_dwordx2 v[42:43], v[58:59], off offset:128

; #define EGAS __attribute__((address_space(1)))
; __device__ __forceinline__ float sigm(float x) { return __builtin_amdgcn_rcpf(1.f + __expf(-x)); }
;     __device__ __forceinline__ void operator()(const f32x4 (&acc)[2][2][4][2], const Unit& u, int wr, int wc, int fr, int fq) const {
;     ...
;                 for (int bj = 0; bj < 2; ++bj) {
;                     f32x4 v0 = acc[ai][bj][m][0], v1 = acc[ai][bj][m][1];
;                     if constexpr (MODE == EP_IN || MODE == EP_U) { v0 = v0 * rs[ai][m]; v1 = v1 * rs[ai][m]; }
;                     const int ct = bj * HALF + cw;
;                     if constexpr (MODE == EP_IN) {
;                         if (pn < 12) {
;                             rope8(v0, v1, WSF(WS_ROPEA) + (row * 64 + (cw >> 1)) * 2);
;                             EGAS bf16_t* O = pn < 6 ? WSB(WS_QA) : WSB(WS_KA); const int c = (pn < 6 ? pn : pn - 6) * 256 + ct;
;                             st8(O + row * WA + c, v0, v1);
;                         } else if (pn < 18) { st8(WSB(WS_VA) + row * WA + (pn - 12) * 256 + ct, v0, v1);
;                         } else if (pn < 20) { st8(WSB(WS_QL) + row * QLORA + (pn - 18) * 256 + ct, v0, v1);
;                         } else if (pn < 22) { st8(WSB(WS_KVL) + row * KVLORA + (pn - 20) * 256 + ct, v0, v1);
;                         } else if (pn < 38) {
;                             const int gc = (pn - 22) * 256 + ct; const EGAS float* bg = (const EGAS float*)p.f0; const f32x4 b0 = *(const EGAS f32x4*)(bg + gc), b1 = *(const EGAS f32x4*)(bg + gc + 4);
; #pragma unroll
;                             for (int e = 0; e < 4; ++e) { v0[e] = sigm(v0[e] + b0[e]); v1[e] = sigm(v1[e] + b1[e]); }
;                             st8f8(WS8(WS_GATES) + row * 4096 + gc, v0, v1);
.LBB0_938:
	v_mov_b32_e32 v153, v152
	s_nop 0
	v_mov_b32_e32 v26, v152
	v_mov_b32_e32 v27, v152
	v_pk_mul_f32 v[24:25], v[24:25], v[26:27]
	v_pk_mul_f32 v[22:23], v[22:23], v[152:153]
	v_pk_mul_f32 v[20:21], v[20:21], v[26:27]
	v_pk_mul_f32 v[18:19], v[18:19], v[152:153]
	s_and_b64 vcc, exec, s[44:45]
	s_mov_b64 s[36:37], -1
	s_cbranch_vccnz .LBB0_954
	s_and_b64 vcc, exec, s[42:43]
	s_cbranch_vccnz .LBB0_951
	s_andn2_b64 vcc, exec, s[30:31]
	s_cbranch_vccnz .LBB0_948
	s_andn2_b64 vcc, exec, s[28:29]
	s_cbranch_vccnz .LBB0_945
	s_andn2_b64 vcc, exec, s[26:27]
	s_cbranch_vccnz .LBB0_944
	v_add_u32_e32 v40, s19, v138
	v_mov_b32_e32 v41, v1
	v_mov_b32_e32 v42, v1
	v_mov_b32_e32 v43, v1
	v_add_f32_e32 v26, v22, v224
	v_add_f32_e32 v30, v18, v228
	v_add_f32_e32 v27, v23, v225
	v_add_f32_e32 v31, v19, v229
	v_mul_f32_e32 v26, 0xbfb8aa3b, v26
	v_mul_f32_e32 v30, 0xbfb8aa3b, v30
	v_mul_f32_e32 v27, 0xbfb8aa3b, v27
	v_mul_f32_e32 v31, 0xbfb8aa3b, v31
	v_exp_f32_e32 v26, v26
	v_exp_f32_e32 v30, v30
	v_exp_f32_e32 v27, v27
	v_exp_f32_e32 v31, v31
	v_add_f32_e32 v28, v24, v226
	v_add_f32_e32 v32, v20, v230
	v_add_f32_e32 v29, v25, v227
	v_add_f32_e32 v33, v21, v231
	v_mul_f32_e32 v28, 0xbfb8aa3b, v28
	v_mul_f32_e32 v32, 0xbfb8aa3b, v32
	v_mul_f32_e32 v29, 0xbfb8aa3b, v29
	v_mul_f32_e32 v33, 0xbfb8aa3b, v33
	v_exp_f32_e32 v28, v28
	v_exp_f32_e32 v32, v32
	v_exp_f32_e32 v29, v29
	v_exp_f32_e32 v33, v33
	v_add_f32_e32 v26, 1.0, v26
	v_add_f32_e32 v30, 1.0, v30
	v_add_f32_e32 v27, 1.0, v27
	v_add_f32_e32 v31, 1.0, v31
	v_rcp_f32_e32 v26, v26
	v_rcp_f32_e32 v30, v30
	v_rcp_f32_e32 v27, v27
	v_rcp_f32_e32 v31, v31
	v_add_f32_e32 v28, 1.0, v28
	v_add_f32_e32 v32, 1.0, v32
	v_add_f32_e32 v29, 1.0, v29
	v_add_f32_e32 v33, 1.0, v33
	v_rcp_f32_e32 v28, v28
	v_rcp_f32_e32 v32, v32
	v_rcp_f32_e32 v29, v29
	v_rcp_f32_e32 v33, v33
	v_cvt_pk_fp8_f32 v42, v26, v27
	v_cvt_pk_fp8_f32 v43, v30, v31
	v_lshl_add_u64 v[26:27], s[54:55], 0, v[0:1]
	v_lshl_add_u64 v[26:27], v[26:27], 0, v[40:41]
	v_cvt_pk_fp8_f32 v42, v28, v29 op_sel:[0, 0, 1]
	v_cvt_pk_fp8_f32 v43, v32, v33 op_sel:[0, 0, 1]
	global_store_dwordx2 v[26:27], v[42:43], off offset:128

; #define EGAS __attribute__((address_space(1)))
; __device__ __forceinline__ float sigm(float x) { return __builtin_amdgcn_rcpf(1.f + __expf(-x)); }
; __device__ __forceinline__ void st8f8(EGAS unsigned char* dst, f32x4 v0, f32x4 v1) {
;     int w0 = __builtin_amdgcn_cvt_pk_fp8_f32(v0[0], v0[1], 0, false); w0 = __builtin_amdgcn_cvt_pk_fp8_f32(v0[2], v0[3], w0, true);
;     int w1 = __builtin_amdgcn_cvt_pk_fp8_f32(v1[0], v1[1], 0, false); w1 = __builtin_amdgcn_cvt_pk_fp8_f32(v1[2], v1[3], w1, true);
;     *(EGAS u32x2e*)dst = (u32x2e){(unsigned)w0, (unsigned)w1}; }
;     __device__ __forceinline__ void operator()(const f32x4 (&acc)[2][2][4][2], const Unit& u, int wr, int wc, int fr, int fq) const {
;     ...
;                         } else if (pn < 38) {
;                             const int gc = (pn - 22) * 256 + ct; const EGAS float* bg = (const EGAS float*)p.f0; const f32x4 b0 = *(const EGAS f32x4*)(bg + gc), b1 = *(const EGAS f32x4*)(bg + gc + 4);
; #pragma unroll
;                             for (int e = 0; e < 4; ++e) { v0[e] = sigm(v0[e] + b0[e]); v1[e] = sigm(v1[e] + b1[e]); }
;                             st8f8(WS8(WS_GATES) + row * 4096 + gc, v0, v1);
.LBB0_981:
	s_and_b64 vcc, exec, s[42:43]
	s_cbranch_vccnz .LBB0_993
	s_andn2_b64 vcc, exec, s[30:31]
	s_mov_b64 s[30:31], -1
	s_cbranch_vccnz .LBB0_990
	s_andn2_b64 vcc, exec, s[28:29]
	s_mov_b64 s[28:29], -1
	s_cbranch_vccnz .LBB0_987
	s_andn2_b64 vcc, exec, s[26:27]
	s_cbranch_vccnz .LBB0_986
	v_add_u32_e32 v24, s19, v138
	v_mov_b32_e32 v25, v1
	v_mov_b32_e32 v26, v1
	v_mov_b32_e32 v27, v1
	v_add_f32_e32 v10, v6, v224
	v_add_f32_e32 v14, v2, v228
	v_add_f32_e32 v11, v7, v225
	v_add_f32_e32 v15, v3, v229
	v_mul_f32_e32 v10, 0xbfb8aa3b, v10
	v_mul_f32_e32 v14, 0xbfb8aa3b, v14
	v_mul_f32_e32 v11, 0xbfb8aa3b, v11
	v_mul_f32_e32 v15, 0xbfb8aa3b, v15
	v_exp_f32_e32 v10, v10
	v_exp_f32_e32 v14, v14
	v_exp_f32_e32 v11, v11
	v_exp_f32_e32 v15, v15
	v_add_f32_e32 v12, v8, v226
	v_add_f32_e32 v16, v4, v230
	v_add_f32_e32 v13, v9, v227
	v_add_f32_e32 v17, v5, v231
	v_mul_f32_e32 v12, 0xbfb8aa3b, v12
	v_mul_f32_e32 v16, 0xbfb8aa3b, v16
	v_mul_f32_e32 v13, 0xbfb8aa3b, v13
	v_mul_f32_e32 v17, 0xbfb8aa3b, v17
	v_exp_f32_e32 v12, v12
	v_exp_f32_e32 v16, v16
	v_exp_f32_e32 v13, v13
	v_exp_f32_e32 v17, v17
	v_add_f32_e32 v10, 1.0, v10
	v_add_f32_e32 v14, 1.0, v14
	v_add_f32_e32 v11, 1.0, v11
	v_add_f32_e32 v15, 1.0, v15
	v_rcp_f32_e32 v10, v10
	v_rcp_f32_e32 v14, v14
	v_rcp_f32_e32 v11, v11
	v_rcp_f32_e32 v15, v15
	v_add_f32_e32 v12, 1.0, v12
	v_add_f32_e32 v16, 1.0, v16
	v_add_f32_e32 v13, 1.0, v13
	v_add_f32_e32 v17, 1.0, v17
	v_rcp_f32_e32 v12, v12
	v_rcp_f32_e32 v16, v16
	v_rcp_f32_e32 v13, v13
	v_rcp_f32_e32 v17, v17
	v_cvt_pk_fp8_f32 v26, v10, v11
	v_cvt_pk_fp8_f32 v27, v14, v15
	v_lshl_add_u64 v[10:11], s[54:55], 0, v[0:1]
	v_lshl_add_u64 v[10:11], v[10:11], 0, v[24:25]
	v_cvt_pk_fp8_f32 v26, v12, v13 op_sel:[0, 0, 1]
	v_cvt_pk_fp8_f32 v27, v16, v17 op_sel:[0, 0, 1]
	global_store_dwordx2 v[10:11], v[26:27], off offset:128
